# attention K tile staged row-major with source-side XOR swizzle: each K tile DMA touches 8 full 128-B lines instead of 64 partial ones; fragment reads follow (3 v_xor per step)
# baseline (speedup 1.0000x reference)
.LBB0_969:
	s_sub_i32 s2, 1, s90
	s_and_b64 s[0:1], s[8:9], exec
	s_cselect_b32 s0, s2, s90
	v_mov_b32_e32 v52, v0
	s_cmp_eq_u32 s0, 0
	s_cselect_b32 s82, s12, s13
	v_readfirstlane_b32 s41, v52
	s_ashr_i32 s91, s41, 6
	s_lshl_b32 s43, s82, 8
	s_lshl_b32 s6, s91, 5
	s_or_b32 s0, s10, s43
	s_ashr_i32 s1, s6, 31
	s_add_u32 s38, s0, s6
	s_addc_u32 s39, s11, s1
	s_lshl_b64 s[0:1], s[38:39], 10
	v_and_b32_e32 v223, 63, v52
	s_add_u32 s0, s14, s0
	s_addc_u32 s1, s15, s1
	v_lshrrev_b32_e32 v226, 3, v223
	v_lshl_add_u32 v226, s91, 3, v226
	v_lshrrev_b32_e32 v227, 4, v223
	v_mov_b32_e32 v224, s91
	v_and_b32_e32 v224, 1, v224
	v_lshl_add_u32 v227, v224, 2, v227
	v_and_b32_e32 v224, 7, v223
	v_xor_b32_e32 v227, v227, v224
	v_lshlrev_b32_e32 v227, 4, v227
	v_lshl_or_b32 v224, v226, 10, v227
	s_mov_b32 s2, 0
	v_lshl_add_u64 v[2:3], s[18:19], 0, v[224:225]
	s_ashr_i32 s3, s2, 31
	v_lshl_add_u64 v[226:227], s[2:3], 1, v[2:3]
	s_lshl_b32 s2, s91, 4
	v_bfe_u32 v220, v52, 2, 4
	v_and_or_b32 v2, s2, 48, v220
	s_ashr_i32 s2, s41, 3
	s_and_b32 s4, s2, 0xffffffe0
	v_lshlrev_b32_e32 v224, 10, v2
	s_ashr_i32 s5, s4, 31
	v_lshlrev_b32_e32 v235, 3, v52
	s_lshl_b32 s2, s91, 10
	v_lshl_add_u64 v[2:3], s[20:21], 0, v[224:225]
	v_and_b32_e32 v53, 24, v235
	s_cmp_lg_u32 0, -1
	v_lshl_add_u64 v[2:3], s[4:5], 1, v[2:3]
	v_lshlrev_b32_e32 v224, 1, v53
	s_cselect_b32 s3, 0, 0
	v_lshl_add_u64 v[50:51], v[2:3], 0, v[224:225]
	s_add_i32 s83, s2, s3
	s_mov_b32 s3, m0
	s_mov_b32 m0, s83
	s_nop 0
	global_load_lds_dwordx4 v[226:227], off
	s_mov_b32 m0, s3
	s_mov_b64 s[16:17], 0x80
	s_add_i32 s84, s83, 0x6000
	s_mov_b32 s3, m0
	s_mov_b32 m0, s84
	s_nop 0
	global_load_lds_dwordx4 v[50:51], off
	s_mov_b32 m0, s3
	v_lshl_add_u64 v[2:3], v[50:51], 0, s[16:17]
	v_and_b32_e32 v234, 31, v52
	s_add_i32 s3, s83, 0x8000
	s_mov_b32 s16, m0
	s_mov_b32 m0, s3
	s_nop 0
	global_load_lds_dwordx4 v[2:3], off
	s_mov_b32 m0, s16
	v_lshl_add_u64 v[2:3], v[226:227], 0, s[24:25]
	v_bfe_u32 v221, v52, 5, 1
	s_add_i32 s3, s83, 0x2000
	s_mov_b32 s16, m0
	s_mov_b32 m0, s3
	s_nop 0
	global_load_lds_dwordx4 v[2:3], off
	s_mov_b32 m0, s16
	v_lshlrev_b32_e32 v2, 10, v234
	v_lshl_or_b32 v3, v221, 4, v2
	global_load_dwordx4 v[174:177], v3, s[0:1]
	global_load_dwordx4 v[170:173], v3, s[0:1] offset:32
	global_load_dwordx4 v[166:169], v3, s[0:1] offset:64
	global_load_dwordx4 v[162:165], v3, s[0:1] offset:96
	v_mov_b32_e32 v2, 0
	v_mov_b32_e32 v18, v225
	v_lshlrev_b32_e32 v4, 7, v234
	v_bfe_u32 v5, v234, 1, 3
	v_xor_b32_e32 v5, v5, v221
	v_lshl_or_b32 v241, v5, 4, v4
	v_lshl_add_u64 v[4:5], v[226:227], 0, s[26:27]
	s_add_i32 s3, s83, 0x4000
	s_mov_b32 s0, m0
	s_mov_b32 m0, s3
	s_nop 0
	global_load_lds_dwordx4 v[4:5], off
	s_mov_b32 m0, s0
	s_waitcnt vmcnt(3) lgkmcnt(0)
	s_barrier
	ds_read_b128 v[4:7], v241
	v_mov_b32_e32 v19, v18
	v_mov_b32_e32 v20, v18
	v_mov_b32_e32 v21, v18
	v_mov_b32_e32 v22, v18
	v_mov_b32_e32 v23, v18
	v_mov_b32_e32 v24, v18
	v_mov_b32_e32 v25, v18
	v_mov_b32_e32 v26, v18
	v_mov_b32_e32 v27, v18
	v_mov_b32_e32 v28, v18
	v_mov_b32_e32 v29, v18
	v_mov_b32_e32 v30, v18
	v_mov_b32_e32 v31, v18
	v_mov_b32_e32 v32, v18
	v_mov_b32_e32 v33, v18
	s_cmp_lg_u32 s82, 0
	s_cselect_b64 s[0:1], -1, 0
	v_lshlrev_b32_e32 v236, 2, v221
	v_or_b32_e32 v239, s6, v234
	s_and_b64 vcc, exec, s[0:1]
	s_waitcnt vmcnt(3) lgkmcnt(0)
	v_mfma_f32_32x32x16_bf16 v[34:49], v[4:7], v[174:177], v[18:33]
	ds_read_b128 v[4:7], v241 offset:4096
	s_waitcnt lgkmcnt(0)
	v_mfma_f32_32x32x16_bf16 v[18:33], v[4:7], v[174:177], v[18:33]
	v_xor_b32_e32 v241, 32, v241
	ds_read_b128 v[4:7], v241
	s_waitcnt vmcnt(2) lgkmcnt(0)
	v_mfma_f32_32x32x16_bf16 v[34:49], v[4:7], v[170:173], v[34:49]
	ds_read_b128 v[4:7], v241 offset:4096
	s_waitcnt lgkmcnt(0)
	v_mfma_f32_32x32x16_bf16 v[18:33], v[4:7], v[170:173], v[18:33]
	v_xor_b32_e32 v241, 0x60, v241
	ds_read_b128 v[4:7], v241
	s_waitcnt vmcnt(1) lgkmcnt(0)
	v_mfma_f32_32x32x16_bf16 v[34:49], v[4:7], v[166:169], v[34:49]
	ds_read_b128 v[4:7], v241 offset:4096
	s_waitcnt lgkmcnt(0)
	v_mfma_f32_32x32x16_bf16 v[18:33], v[4:7], v[166:169], v[18:33]
	v_xor_b32_e32 v241, 32, v241
	ds_read_b128 v[4:7], v241
	s_waitcnt vmcnt(0) lgkmcnt(0)
	v_mfma_f32_32x32x16_bf16 v[34:49], v[4:7], v[162:165], v[34:49]
	ds_read_b128 v[4:7], v241 offset:4096
	v_xor_b32_e32 v241, 0x60, v241
	s_waitcnt lgkmcnt(0)
	v_mfma_f32_32x32x16_bf16 v[18:33], v[4:7], v[162:165], v[18:33]
	s_nop 15
	s_nop 7
	s_cbranch_vccnz .LBB0_971
	v_lshlrev_b32_e32 v3, 2, v221
	v_or_b32_e32 v5, 32, v3
	v_subrev_u32_e32 v4, s43, v3
	v_cmp_le_i32_e32 vcc, v5, v239
	s_nop 6
	v_cndmask_b32_e32 v18, v1, v18, vcc
	v_cmp_lt_i32_e32 vcc, v4, v239
	s_nop 1
	v_cndmask_b32_e32 v35, v1, v35, vcc
	v_cmp_le_i32_e32 vcc, v4, v239
	v_or_b32_e32 v4, 33, v3
	s_nop 0
	v_cndmask_b32_e32 v34, v1, v34, vcc
	v_cmp_le_i32_e32 vcc, v4, v239
	v_or_b32_e32 v4, 2, v3
	s_nop 0
	v_cndmask_b32_e32 v19, v1, v19, vcc
	v_cmp_le_i32_e32 vcc, v4, v239
	v_or_b32_e32 v4, 34, v3
	s_nop 0
	v_cndmask_b32_e32 v36, v1, v36, vcc
	v_cmp_le_i32_e32 vcc, v4, v239
	v_or_b32_e32 v4, 3, v3
	s_nop 0
	v_cndmask_b32_e32 v20, v1, v20, vcc
	v_cmp_le_i32_e32 vcc, v4, v239
	v_or_b32_e32 v4, 35, v3
	s_nop 0
	v_cndmask_b32_e32 v37, v1, v37, vcc
	v_cmp_le_i32_e32 vcc, v4, v239
	v_or_b32_e32 v4, 8, v3
	s_nop 0
	v_cndmask_b32_e32 v21, v1, v21, vcc
	v_cmp_le_i32_e32 vcc, v4, v239
	v_or_b32_e32 v4, 40, v3
	s_nop 0
	v_cndmask_b32_e32 v38, v1, v38, vcc
	v_cmp_le_i32_e32 vcc, v4, v239
	v_or_b32_e32 v4, 9, v3
	s_nop 0
	v_cndmask_b32_e32 v22, v1, v22, vcc
	v_cmp_le_i32_e32 vcc, v4, v239
	v_or_b32_e32 v4, 41, v3
	s_nop 0
	v_cndmask_b32_e32 v39, v1, v39, vcc
	v_cmp_le_i32_e32 vcc, v4, v239
	v_or_b32_e32 v4, 10, v3
	s_nop 0
	v_cndmask_b32_e32 v23, v1, v23, vcc
	v_cmp_le_i32_e32 vcc, v4, v239
	v_or_b32_e32 v4, 42, v3
	s_nop 0
	v_cndmask_b32_e32 v40, v1, v40, vcc
	v_cmp_le_i32_e32 vcc, v4, v239
	v_or_b32_e32 v4, 11, v3
	s_nop 0
	v_cndmask_b32_e32 v24, v1, v24, vcc
	v_cmp_le_i32_e32 vcc, v4, v239
	v_or_b32_e32 v4, 43, v3
	s_nop 0
	v_cndmask_b32_e32 v41, v1, v41, vcc
	v_cmp_le_i32_e32 vcc, v4, v239
	v_or_b32_e32 v4, 16, v3
	s_nop 0
	v_cndmask_b32_e32 v25, v1, v25, vcc
	v_cmp_le_i32_e32 vcc, v4, v239
	v_or_b32_e32 v4, 48, v3
	s_nop 0
	v_cndmask_b32_e32 v42, v1, v42, vcc
	v_cmp_le_i32_e32 vcc, v4, v239
	v_or_b32_e32 v4, 17, v3
	s_nop 0
	v_cndmask_b32_e32 v26, v1, v26, vcc
	v_cmp_le_i32_e32 vcc, v4, v239
	v_or_b32_e32 v4, 49, v3
	s_nop 0
	v_cndmask_b32_e32 v43, v1, v43, vcc
	v_cmp_le_i32_e32 vcc, v4, v239
	v_or_b32_e32 v4, 18, v3
	s_nop 0
	v_cndmask_b32_e32 v27, v1, v27, vcc
	v_cmp_le_i32_e32 vcc, v4, v239
	v_or_b32_e32 v4, 50, v3
	s_nop 0
	v_cndmask_b32_e32 v44, v1, v44, vcc
	v_cmp_le_i32_e32 vcc, v4, v239
	v_or_b32_e32 v4, 19, v3
	s_nop 0
	v_cndmask_b32_e32 v28, v1, v28, vcc
	v_cmp_le_i32_e32 vcc, v4, v239
	v_or_b32_e32 v4, 51, v3
	s_nop 0
	v_cndmask_b32_e32 v45, v1, v45, vcc
	v_cmp_le_i32_e32 vcc, v4, v239
	v_or_b32_e32 v4, 24, v3
	s_nop 0
	v_cndmask_b32_e32 v29, v1, v29, vcc
	v_cmp_le_i32_e32 vcc, v4, v239
	v_or_b32_e32 v4, 56, v3
	s_nop 0
	v_cndmask_b32_e32 v46, v1, v46, vcc
	v_cmp_le_i32_e32 vcc, v4, v239
	v_or_b32_e32 v4, 25, v3
	s_nop 0
	v_cndmask_b32_e32 v30, v1, v30, vcc
	v_cmp_le_i32_e32 vcc, v4, v239
	v_or_b32_e32 v4, 57, v3
	s_nop 0
	v_cndmask_b32_e32 v47, v1, v47, vcc
	v_cmp_le_i32_e32 vcc, v4, v239
	v_or_b32_e32 v4, 26, v3
	s_nop 0
	v_cndmask_b32_e32 v31, v1, v31, vcc
	v_cmp_le_i32_e32 vcc, v4, v239
	v_or_b32_e32 v4, 58, v3
	s_nop 0
	v_cndmask_b32_e32 v48, v1, v48, vcc
	v_cmp_le_i32_e32 vcc, v4, v239
	v_or_b32_e32 v4, 27, v3
	v_or_b32_e32 v3, 59, v3
	v_cndmask_b32_e32 v32, v1, v32, vcc
	v_cmp_le_i32_e32 vcc, v4, v239
	s_nop 1
	v_cndmask_b32_e32 v49, v1, v49, vcc
	v_cmp_le_i32_e32 vcc, v3, v239
	s_nop 1
	v_cndmask_b32_e32 v33, v1, v33, vcc
.LBB0_971:
	s_and_b32 s16, s41, 0x3fffffc0
	s_cmp_lg_u32 0, -1
	v_lshlrev_b32_e32 v3, 1, v52
	s_cselect_b32 s3, 0, 0
	v_lshlrev_b32_e32 v4, 4, v52
	v_and_b32_e32 v3, 32, v3
	s_add_i32 s17, s3, 0x6000
	v_and_b32_e32 v4, 0xc0, v4
	v_add_u32_e32 v54, s17, v3
	v_lshl_or_b32 v55, v221, 8, v4
	v_add_u32_e32 v3, 0, v3
	v_add3_u32 v242, v3, v53, v55
	v_add3_u32 v238, v54, v53, v55
	v_max3_f32 v53, v34, v35, v18
	v_max3_f32 v54, v36, v37, v19
	s_lshl_b32 s16, s16, 2
	v_max3_f32 v53, v53, v20, v21
	v_max3_f32 v54, v54, v40, v41
	s_add_i32 s94, s16, 0
	v_max3_f32 v53, v53, v38, v39
	v_max3_f32 v54, v54, v24, v25
	s_add_i32 s17, s43, 0x100
	v_max3_f32 v53, v53, v22, v23
	v_max3_f32 v54, v54, v44, v45
	s_add_i32 s94, s94, 0x12000
	v_max3_f32 v53, v53, v42, v43
	v_max3_f32 v54, v54, v28, v29
	s_mov_b32 s6, 1
	v_max3_f32 v53, v53, v26, v27
	v_max3_f32 v54, v54, v48, v49
	s_mov_b32 s44, 0
	v_max3_f32 v53, v53, v46, v47
	v_max3_f32 v54, v54, v32, v33
	v_mov_b32_e32 v3, v2
	v_max3_f32 v53, v53, v30, v31
	v_mov_b32_e32 v4, v2
	v_max_f32_e32 v53, v53, v54
	v_mov_b32_e32 v5, v2
	v_mov_b32_e32 v54, v53
	s_nop 1
	v_permlane32_swap_b32_e32 v53, v54
	v_max_f32_e32 v53, v53, v54
	v_mov_b32_e32 v6, v2
	v_add_f32_e32 v240, v225, v53
	v_sub_f32_e32 v18, v18, v53
	v_sub_f32_e32 v19, v19, v53
	v_sub_f32_e32 v34, v34, v53
	v_sub_f32_e32 v35, v35, v53
	v_sub_f32_e32 v36, v36, v53
	s_nop 0
	v_xor_b32_e32 v66, 0x80000000, v240
	v_mov_b32_e32 v67, v66
	v_mov_b32_e32 v68, v66
	v_mov_b32_e32 v69, v66
	v_mov_b32_e32 v70, v66
	v_mov_b32_e32 v71, v66
	v_mov_b32_e32 v72, v66
	v_mov_b32_e32 v73, v66
	v_mov_b32_e32 v74, v66
	v_mov_b32_e32 v75, v66
	v_mov_b32_e32 v76, v66
	v_mov_b32_e32 v77, v66
	v_mov_b32_e32 v78, v66
	v_mov_b32_e32 v79, v66
	v_mov_b32_e32 v80, v66
	v_mov_b32_e32 v81, v66
	s_waitcnt vmcnt(0) lgkmcnt(0)
	s_barrier
	v_exp_f32_e32 v82, v18
	v_exp_f32_e32 v83, v19
	v_lshl_add_u64 v[18:19], v[226:227], 0, s[28:29]
	s_mov_b32 s16, m0
	s_mov_b32 m0, s83
	s_nop 0
	global_load_lds_dwordx4 v[18:19], off
	s_mov_b32 m0, s16
	s_add_i32 s16, s3, s2
	v_lshl_add_u64 v[18:19], v[50:51], 0, s[24:25]
	s_add_i32 s2, s16, 0xa000
	s_mov_b32 s3, m0
	s_mov_b32 m0, s2
	s_nop 0
	global_load_lds_dwordx4 v[18:19], off
	s_mov_b32 m0, s3
	s_mov_b64 s[2:3], 0x10080
	v_lshl_add_u64 v[18:19], v[50:51], 0, s[2:3]
	s_add_i32 s16, s16, 0xc000
	s_mov_b32 s2, m0
	s_mov_b32 m0, s16
	s_nop 0
	global_load_lds_dwordx4 v[18:19], off
	s_mov_b32 m0, s2
	ds_read_b128 v[206:209], v241 offset:8192
	ds_read_b128 v[202:205], v241 offset:12288
	v_xor_b32_e32 v241, 32, v241
	ds_read_b128 v[198:201], v241 offset:8192
	ds_read_b128 v[194:197], v241 offset:12288
	v_xor_b32_e32 v241, 0x60, v241
	ds_read_b128 v[190:193], v241 offset:8192
	ds_read_b128 v[186:189], v241 offset:12288
	v_xor_b32_e32 v241, 32, v241
	ds_read_b128 v[182:185], v241 offset:8192
	ds_read_b128 v[178:181], v241 offset:12288
	v_xor_b32_e32 v241, 0x60, v241
	v_sub_f32_e32 v20, v20, v53
	v_sub_f32_e32 v37, v37, v53
	v_sub_f32_e32 v21, v21, v53
	v_sub_f32_e32 v38, v38, v53
	v_sub_f32_e32 v22, v22, v53
	v_sub_f32_e32 v39, v39, v53
	v_sub_f32_e32 v23, v23, v53
	v_sub_f32_e32 v40, v40, v53
	v_sub_f32_e32 v24, v24, v53
	v_sub_f32_e32 v41, v41, v53
	v_sub_f32_e32 v25, v25, v53
	v_sub_f32_e32 v42, v42, v53
	v_sub_f32_e32 v26, v26, v53
	v_sub_f32_e32 v43, v43, v53
	v_sub_f32_e32 v27, v27, v53
	v_sub_f32_e32 v44, v44, v53
	v_sub_f32_e32 v28, v28, v53
	v_sub_f32_e32 v45, v45, v53
	v_sub_f32_e32 v29, v29, v53
	v_sub_f32_e32 v46, v46, v53
	v_sub_f32_e32 v30, v30, v53
	v_sub_f32_e32 v47, v47, v53
	v_sub_f32_e32 v31, v31, v53
	v_sub_f32_e32 v48, v48, v53
	v_sub_f32_e32 v32, v32, v53
	v_sub_f32_e32 v49, v49, v53
	v_sub_f32_e32 v33, v33, v53
	v_exp_f32_e32 v98, v34
	v_exp_f32_e32 v99, v35
	v_exp_f32_e32 v100, v36
	v_exp_f32_e32 v101, v37
	v_exp_f32_e32 v102, v38
	v_exp_f32_e32 v103, v39
	v_exp_f32_e32 v104, v40
	v_exp_f32_e32 v105, v41
	v_exp_f32_e32 v106, v42
	v_exp_f32_e32 v107, v43
	v_exp_f32_e32 v108, v44
	v_exp_f32_e32 v109, v45
	v_exp_f32_e32 v110, v46
	v_exp_f32_e32 v111, v47
	v_exp_f32_e32 v112, v48
	v_exp_f32_e32 v113, v49
	v_exp_f32_e32 v84, v20
	v_exp_f32_e32 v85, v21
	v_exp_f32_e32 v86, v22
	v_exp_f32_e32 v87, v23
	v_exp_f32_e32 v88, v24
	v_exp_f32_e32 v89, v25
	v_exp_f32_e32 v90, v26
	v_exp_f32_e32 v91, v27
	v_exp_f32_e32 v92, v28
	v_exp_f32_e32 v93, v29
	v_exp_f32_e32 v94, v30
	v_exp_f32_e32 v95, v31
	v_exp_f32_e32 v96, v32
	v_exp_f32_e32 v97, v33
	s_waitcnt vmcnt(3) lgkmcnt(0)
	s_barrier
	v_and_b32_e32 v18, 3, v52
	v_mov_b32_e32 v7, v2
	v_mov_b32_e32 v8, v2
	v_mov_b32_e32 v9, v2
	v_mov_b32_e32 v10, v2
	v_mov_b32_e32 v11, v2
	v_mov_b32_e32 v12, v2
	v_mov_b32_e32 v13, v2
	v_mov_b32_e32 v14, v2
	v_mov_b32_e32 v15, v2
	v_mov_b32_e32 v16, v2
	v_mov_b32_e32 v17, v2
	s_lshr_b32 s95, s17, 6
	s_andn2_b64 vcc, exec, s[0:1]
	v_cmp_gt_u32_e64 s[0:1], 32, v223
	v_lshlrev_b32_e32 v243, 4, v221
	v_lshl_add_u32 v237, v234, 2, s94
	v_lshlrev_b32_e32 v224, 4, v18
	s_cbranch_vccnz .LBB0_987
	s_lshl_b32 s2, s41, 8
	s_and_b32 s2, s2, 0xc000
	v_lshl_add_u64 v[18:19], s[4:5], 1, v[224:225]
	v_lshl_or_b32 v20, v220, 10, s2
	v_mov_b32_e32 v21, v225
	v_lshl_add_u64 v[18:19], v[18:19], 0, v[20:21]
	v_lshl_add_u64 v[214:215], s[22:23], 0, v[18:19]
	v_mov_b64_e32 v[64:65], v[16:17]
	v_mov_b64_e32 v[48:49], v[16:17]
	v_mov_b64_e32 v[32:33], v[16:17]
	s_add_i32 s42, s95, -5
	s_movk_i32 s46, 0x2000
	v_add_u32_e32 v228, 0x2000, v238
	s_movk_i32 s44, 0x4000
	s_mov_b32 s2, 0
	v_mov_b32_e32 v244, 0
	s_mov_b64 s[16:17], 0
	v_mov_b64_e32 v[62:63], v[14:15]
	v_mov_b64_e32 v[60:61], v[12:13]
	v_mov_b64_e32 v[58:59], v[10:11]
	v_mov_b64_e32 v[56:57], v[8:9]
	v_mov_b64_e32 v[54:55], v[6:7]
	v_mov_b64_e32 v[52:53], v[4:5]
	v_mov_b64_e32 v[50:51], v[2:3]
	v_mov_b64_e32 v[46:47], v[14:15]
	v_mov_b64_e32 v[44:45], v[12:13]
	v_mov_b64_e32 v[42:43], v[10:11]
	v_mov_b64_e32 v[40:41], v[8:9]
	v_mov_b64_e32 v[38:39], v[6:7]
	v_mov_b64_e32 v[36:37], v[4:5]
	v_mov_b64_e32 v[34:35], v[2:3]
	v_mov_b64_e32 v[30:31], v[14:15]
	v_mov_b64_e32 v[28:29], v[12:13]
	v_mov_b64_e32 v[26:27], v[10:11]
	v_mov_b64_e32 v[24:25], v[8:9]
	v_mov_b64_e32 v[22:23], v[6:7]
	v_mov_b64_e32 v[20:21], v[4:5]
	v_mov_b64_e32 v[18:19], v[2:3]
	v_readfirstlane_b32 s98, v226
	v_readfirstlane_b32 s99, v227
	v_readfirstlane_b32 s100, v214
	v_readfirstlane_b32 s101, v215
	s_sub_u32 s98, s98, 64
	s_subb_u32 s99, s99, 0
	s_mov_b32 s3, 0
	v_subrev_u32_e32 v218, s98, v226
	v_subrev_u32_e32 v219, s100, v214
	s_add_u32 s98, s98, s16
	s_addc_u32 s99, s99, s17
	s_add_u32 s98, s98, s30
	s_addc_u32 s99, s99, s31
	s_add_u32 s100, s100, s16
	s_addc_u32 s101, s101, s17
	s_add_u32 s100, s100, s34
	s_addc_u32 s101, s101, s35

.LBB0_974:
	ds_read_b128 v[82:85], v94
	ds_read_b128 v[198:201], v94 offset:4096
	v_xor_b32_e32 v94, 32, v94
	ds_read_b128 v[202:205], v94
	ds_read_b128 v[194:197], v94 offset:4096
	s_waitcnt lgkmcnt(4)
	v_mfma_f32_32x32x16_bf16 v[50:65], v[150:153], v[106:109], v[50:65]
	v_exp_f32_e32 v130, v130
	v_exp_f32_e32 v131, v131
	v_exp_f32_e32 v132, v132
	v_xor_b32_e32 v94, 0x60, v94
	ds_read_b128 v[190:193], v94
	ds_read_b128 v[186:189], v94 offset:4096
	v_xor_b32_e32 v94, 32, v94
	ds_read_b128 v[182:185], v94
	ds_read_b128 v[178:181], v94 offset:4096
	ds_read_b64_tr_b16 v[98:99],v102 offset:3072
	ds_read_b64_tr_b16 v[100:101],v102 offset:3584
	ds_read_b64_tr_b16 v[94:95],v102 offset:2048
	ds_read_b64_tr_b16 v[96:97],v102 offset:2560
	v_mfma_f32_32x32x16_bf16 v[34:49], v[150:153], v[110:113], v[34:49]
	v_exp_f32_e32 v133, v133
	v_exp_f32_e32 v134, v134
	v_exp_f32_e32 v135, v135
	v_mfma_f32_32x32x16_bf16 v[50:65], v[146:149], v[86:89], v[50:65]
	v_exp_f32_e32 v136, v136
	v_exp_f32_e32 v137, v137
	v_exp_f32_e32 v138, v138
	ds_read_b64_tr_b16 v[86:87],v102 offset:0
	ds_read_b64_tr_b16 v[88:89],v102 offset:512
	v_mfma_f32_32x32x16_bf16 v[34:49], v[146:149], v[90:93], v[34:49]
	v_exp_f32_e32 v139, v139
	v_exp_f32_e32 v140, v140
	v_exp_f32_e32 v141, v141
	ds_read_b64_tr_b16 v[90:91],v102 offset:1024
	ds_read_b64_tr_b16 v[92:93],v102 offset:1536
	s_waitcnt lgkmcnt(6)
	v_mfma_f32_32x32x16_bf16 v[18:33], v[146:149], v[98:101], v[18:33]
	v_exp_f32_e32 v142, v142
	v_exp_f32_e32 v143, v143
	v_exp_f32_e32 v144, v144
	ds_read_b64_tr_b16 v[98:99],v102 offset:7168
	ds_read_b64_tr_b16 v[100:101],v102 offset:7680
	s_waitcnt lgkmcnt(6)
	v_mfma_f32_32x32x16_bf16 v[18:33], v[150:153], v[94:97], v[18:33]
	v_exp_f32_e32 v145, v145
	v_exp_f32_e32 v114, v114
	v_exp_f32_e32 v115, v115
	ds_read_b64_tr_b16 v[94:95],v102 offset:6144
	ds_read_b64_tr_b16 v[96:97],v102 offset:6656
	s_waitcnt lgkmcnt(6)
	v_mfma_f32_32x32x16_bf16 v[18:33], v[158:161], v[86:89], v[18:33]
	v_exp_f32_e32 v116, v116
	v_exp_f32_e32 v117, v117
	v_exp_f32_e32 v118, v118
	ds_read_b64_tr_b16 v[86:87],v102 offset:4096
	ds_read_b64_tr_b16 v[88:89],v102 offset:4608
	s_waitcnt lgkmcnt(6)
	v_mfma_f32_32x32x16_bf16 v[18:33], v[154:157], v[90:93], v[18:33]
	v_exp_f32_e32 v119, v119
	v_exp_f32_e32 v120, v120
	v_exp_f32_e32 v121, v121
	ds_read_b64_tr_b16 v[90:91],v102 offset:5120
	ds_read_b64_tr_b16 v[92:93],v102 offset:5632
	s_waitcnt lgkmcnt(6)
	v_mfma_f32_32x32x16_bf16 v[2:17], v[146:149], v[98:101], v[2:17]
	v_exp_f32_e32 v122, v122
	v_exp_f32_e32 v123, v123
	s_waitcnt vmcnt(3) lgkmcnt(0)
	s_barrier
	v_mfma_f32_32x32x16_bf16 v[2:17], v[150:153], v[94:97], v[2:17]
	v_exp_f32_e32 v124, v124
	v_exp_f32_e32 v125, v125
	v_mfma_f32_32x32x16_bf16 v[2:17], v[158:161], v[86:89], v[2:17]
	v_exp_f32_e32 v126, v126
	v_exp_f32_e32 v127, v127
	v_mfma_f32_32x32x16_bf16 v[2:17], v[154:157], v[90:93], v[2:17]
	v_exp_f32_e32 v128, v128
	v_exp_f32_e32 v129, v129
	s_cmp_eq_u32 s3, 0
	s_cbranch_scc1 .LBB0_976
	s_waitcnt lgkmcnt(0)
	s_mov_b32 s3, 0
	v_add_u32_e32 v229, s94, v243
	ds_read_b128 v[86:89], v229 offset:96
	ds_read_b128 v[90:93], v229 offset:64
	ds_read_b128 v[94:97], v229 offset:32
	ds_read_b128 v[98:101], v229
	s_waitcnt lgkmcnt(3)
	v_pk_mul_f32 v[62:63], v[62:63], v[86:87]
	s_waitcnt lgkmcnt(2)
	v_pk_mul_f32 v[58:59], v[58:59], v[90:91]
	s_waitcnt lgkmcnt(1)
	v_pk_mul_f32 v[54:55], v[54:55], v[94:95]
	v_pk_mul_f32 v[64:65], v[64:65], v[88:89]
	v_pk_mul_f32 v[60:61], v[60:61], v[92:93]
	v_pk_mul_f32 v[56:57], v[56:57], v[96:97]
	s_waitcnt lgkmcnt(0)
	v_pk_mul_f32 v[52:53], v[52:53], v[100:101]
	v_pk_mul_f32 v[50:51], v[50:51], v[98:99]
	v_pk_mul_f32 v[46:47], v[46:47], v[86:87]
	v_pk_mul_f32 v[42:43], v[42:43], v[90:91]
	v_pk_mul_f32 v[38:39], v[38:39], v[94:95]
	v_pk_mul_f32 v[48:49], v[48:49], v[88:89]
	v_pk_mul_f32 v[44:45], v[44:45], v[92:93]
	v_pk_mul_f32 v[40:41], v[40:41], v[96:97]
	v_pk_mul_f32 v[36:37], v[36:37], v[100:101]
	v_pk_mul_f32 v[34:35], v[34:35], v[98:99]
	v_pk_mul_f32 v[30:31], v[30:31], v[86:87]
	v_pk_mul_f32 v[26:27], v[26:27], v[90:91]
	v_pk_mul_f32 v[22:23], v[22:23], v[94:95]
	v_pk_mul_f32 v[32:33], v[32:33], v[88:89]
	v_pk_mul_f32 v[28:29], v[28:29], v[92:93]
	v_pk_mul_f32 v[24:25], v[24:25], v[96:97]
	v_pk_mul_f32 v[20:21], v[20:21], v[100:101]
	v_pk_mul_f32 v[18:19], v[18:19], v[98:99]
	v_pk_mul_f32 v[14:15], v[14:15], v[86:87]
	v_pk_mul_f32 v[10:11], v[10:11], v[90:91]
	v_pk_mul_f32 v[6:7], v[6:7], v[94:95]
	v_pk_mul_f32 v[16:17], v[16:17], v[88:89]
	v_pk_mul_f32 v[12:13], v[12:13], v[92:93]
	v_pk_mul_f32 v[8:9], v[8:9], v[96:97]
	v_pk_mul_f32 v[4:5], v[4:5], v[100:101]
	v_pk_mul_f32 v[2:3], v[2:3], v[98:99]

.LBB0_977:
	v_add_u32_e32 v126, s40, v241
	ds_read_b128 v[206:209], v126
	ds_read_b128 v[202:205], v126 offset:4096
	v_xor_b32_e32 v126, 32, v126
	ds_read_b128 v[198:201], v126
	ds_read_b128 v[194:197], v126 offset:4096
	s_waitcnt lgkmcnt(4)
	v_mfma_f32_32x32x16_bf16 v[50:65], v[150:153], v[138:141], v[50:65]
	v_exp_f32_e32 v98, v98
	v_exp_f32_e32 v99, v99
	v_exp_f32_e32 v100, v100
	v_xor_b32_e32 v126, 0x60, v126
	ds_read_b128 v[190:193], v126
	ds_read_b128 v[186:189], v126 offset:4096
	v_xor_b32_e32 v126, 32, v126
	ds_read_b128 v[182:185], v126
	ds_read_b128 v[178:181], v126 offset:4096
	ds_read_b64_tr_b16 v[126:127],v130 offset:3072
	ds_read_b64_tr_b16 v[128:129],v130 offset:3584
	v_mfma_f32_32x32x16_bf16 v[34:49], v[150:153], v[114:117], v[34:49]
	v_exp_f32_e32 v101, v101
	v_exp_f32_e32 v102, v102
	v_exp_f32_e32 v103, v103
	ds_read_b64_tr_b16 v[114:115],v130 offset:0
	ds_read_b64_tr_b16 v[116:117],v130 offset:512
	v_mfma_f32_32x32x16_bf16 v[50:65], v[146:149], v[118:121], v[50:65]
	v_exp_f32_e32 v104, v104
	v_exp_f32_e32 v105, v105
	v_exp_f32_e32 v106, v106
	ds_read_b64_tr_b16 v[118:119],v130 offset:1024
	ds_read_b64_tr_b16 v[120:121],v130 offset:1536
	v_mfma_f32_32x32x16_bf16 v[34:49], v[146:149], v[122:125], v[34:49]
	v_exp_f32_e32 v107, v107
	v_exp_f32_e32 v108, v108
	v_exp_f32_e32 v109, v109
	ds_read_b64_tr_b16 v[122:123],v130 offset:2048
	ds_read_b64_tr_b16 v[124:125],v130 offset:2560
	s_waitcnt lgkmcnt(6)
	v_mfma_f32_32x32x16_bf16 v[18:33], v[146:149], v[126:129], v[18:33]
	v_exp_f32_e32 v110, v110
	v_exp_f32_e32 v111, v111
	v_exp_f32_e32 v112, v112
	ds_read_b64_tr_b16 v[126:127],v130 offset:7168
	ds_read_b64_tr_b16 v[128:129],v130 offset:7680
	s_waitcnt lgkmcnt(6)
	v_mfma_f32_32x32x16_bf16 v[18:33], v[158:161], v[114:117], v[18:33]
	v_exp_f32_e32 v113, v113
	v_exp_f32_e32 v82, v82
	v_exp_f32_e32 v83, v83
	ds_read_b64_tr_b16 v[114:115],v130 offset:4096
	ds_read_b64_tr_b16 v[116:117],v130 offset:4608
	s_waitcnt lgkmcnt(6)
	v_mfma_f32_32x32x16_bf16 v[18:33], v[154:157], v[118:121], v[18:33]
	v_exp_f32_e32 v84, v84
	v_exp_f32_e32 v85, v85
	v_exp_f32_e32 v86, v86
	ds_read_b64_tr_b16 v[118:119],v130 offset:5120
	ds_read_b64_tr_b16 v[120:121],v130 offset:5632
	s_waitcnt lgkmcnt(6)
	v_mfma_f32_32x32x16_bf16 v[18:33], v[150:153], v[122:125], v[18:33]
	v_exp_f32_e32 v87, v87
	v_exp_f32_e32 v88, v88
	v_exp_f32_e32 v89, v89
	ds_read_b64_tr_b16 v[122:123],v130 offset:6144
	ds_read_b64_tr_b16 v[124:125],v130 offset:6656
	s_waitcnt lgkmcnt(6)
	v_mfma_f32_32x32x16_bf16 v[2:17], v[146:149], v[126:129], v[2:17]
	v_exp_f32_e32 v90, v90
	v_exp_f32_e32 v91, v91
	s_waitcnt vmcnt(3) lgkmcnt(0)
	s_barrier
	v_mfma_f32_32x32x16_bf16 v[2:17], v[158:161], v[114:117], v[2:17]
	v_exp_f32_e32 v92, v92
	v_exp_f32_e32 v93, v93
	v_mfma_f32_32x32x16_bf16 v[2:17], v[154:157], v[118:121], v[2:17]
	v_exp_f32_e32 v94, v94
	v_exp_f32_e32 v95, v95
	v_mfma_f32_32x32x16_bf16 v[2:17], v[150:153], v[122:125], v[2:17]
	v_exp_f32_e32 v96, v96
	v_exp_f32_e32 v97, v97
	s_cmp_eq_u32 s3, 0
	s_cbranch_scc1 .LBB0_979
	s_waitcnt lgkmcnt(0)
	s_mov_b32 s3, 0
	v_add_u32_e32 v229, s94, v243
	ds_read_b128 v[114:117], v229 offset:96
	ds_read_b128 v[118:121], v229 offset:64
	ds_read_b128 v[122:125], v229 offset:32
	ds_read_b128 v[126:129], v229
	s_waitcnt lgkmcnt(3)
	v_pk_mul_f32 v[62:63], v[62:63], v[114:115]
	s_waitcnt lgkmcnt(2)
	v_pk_mul_f32 v[58:59], v[58:59], v[118:119]
	s_waitcnt lgkmcnt(1)
	v_pk_mul_f32 v[54:55], v[54:55], v[122:123]
	v_pk_mul_f32 v[64:65], v[64:65], v[116:117]
	v_pk_mul_f32 v[60:61], v[60:61], v[120:121]
	v_pk_mul_f32 v[56:57], v[56:57], v[124:125]
	s_waitcnt lgkmcnt(0)
	v_pk_mul_f32 v[52:53], v[52:53], v[128:129]
	v_pk_mul_f32 v[50:51], v[50:51], v[126:127]
	v_pk_mul_f32 v[46:47], v[46:47], v[114:115]
	v_pk_mul_f32 v[42:43], v[42:43], v[118:119]
	v_pk_mul_f32 v[38:39], v[38:39], v[122:123]
	v_pk_mul_f32 v[48:49], v[48:49], v[116:117]
	v_pk_mul_f32 v[44:45], v[44:45], v[120:121]
	v_pk_mul_f32 v[40:41], v[40:41], v[124:125]
	v_pk_mul_f32 v[36:37], v[36:37], v[128:129]
	v_pk_mul_f32 v[34:35], v[34:35], v[126:127]
	v_pk_mul_f32 v[30:31], v[30:31], v[114:115]
	v_pk_mul_f32 v[26:27], v[26:27], v[118:119]
	v_pk_mul_f32 v[22:23], v[22:23], v[122:123]
	v_pk_mul_f32 v[32:33], v[32:33], v[116:117]
	v_pk_mul_f32 v[28:29], v[28:29], v[120:121]
	v_pk_mul_f32 v[24:25], v[24:25], v[124:125]
	v_pk_mul_f32 v[20:21], v[20:21], v[128:129]
	v_pk_mul_f32 v[18:19], v[18:19], v[126:127]
	v_pk_mul_f32 v[14:15], v[14:15], v[114:115]
	v_pk_mul_f32 v[10:11], v[10:11], v[118:119]
	v_pk_mul_f32 v[6:7], v[6:7], v[122:123]
	v_pk_mul_f32 v[16:17], v[16:17], v[116:117]
	v_pk_mul_f32 v[12:13], v[12:13], v[120:121]
	v_pk_mul_f32 v[8:9], v[8:9], v[124:125]
	v_pk_mul_f32 v[4:5], v[4:5], v[128:129]
	v_pk_mul_f32 v[2:3], v[2:3], v[126:127]

.LBB0_1003:
	s_waitcnt lgkmcnt(14)
	v_mfma_f32_32x32x16_bf16 v[50:65], v[158:161], v[210:213], v[50:65]
	v_exp_f32_e32 v130, v130
	v_exp_f32_e32 v131, v131
	v_exp_f32_e32 v132, v132
	v_exp_f32_e32 v133, v133
	s_waitcnt lgkmcnt(12)
	v_mfma_f32_32x32x16_bf16 v[34:49], v[158:161], v[206:209], v[34:49]
	v_exp_f32_e32 v134, v134
	v_exp_f32_e32 v135, v135
	v_exp_f32_e32 v136, v136
	v_exp_f32_e32 v137, v137
	v_add_u32_e32 v94, s45, v241
	ds_read_b128 v[206:209], v94
	ds_read_b128 v[202:205], v94 offset:4096
	s_waitcnt lgkmcnt(12)
	v_mfma_f32_32x32x16_bf16 v[50:65], v[154:157], v[98:101], v[50:65]
	v_exp_f32_e32 v138, v138
	v_exp_f32_e32 v139, v139
	v_exp_f32_e32 v140, v140
	v_exp_f32_e32 v141, v141
	v_xor_b32_e32 v94, 32, v94
	ds_read_b128 v[198:201], v94
	ds_read_b128 v[194:197], v94 offset:4096
	s_waitcnt lgkmcnt(12)
	v_mfma_f32_32x32x16_bf16 v[34:49], v[154:157], v[102:105], v[34:49]
	v_exp_f32_e32 v142, v142
	v_exp_f32_e32 v143, v143
	v_exp_f32_e32 v144, v144
	v_exp_f32_e32 v145, v145
	v_xor_b32_e32 v94, 0x60, v94
	ds_read_b128 v[190:193], v94
	ds_read_b128 v[186:189], v94 offset:4096
	s_waitcnt lgkmcnt(12)
	v_mfma_f32_32x32x16_bf16 v[50:65], v[150:153], v[106:109], v[50:65]
	v_exp_f32_e32 v114, v114
	v_exp_f32_e32 v115, v115
	v_exp_f32_e32 v116, v116
	v_exp_f32_e32 v117, v117
	v_xor_b32_e32 v94, 32, v94
	ds_read_b128 v[182:185], v94
	ds_read_b128 v[178:181], v94 offset:4096
	s_waitcnt lgkmcnt(12)
	v_mfma_f32_32x32x16_bf16 v[34:49], v[150:153], v[82:85], v[34:49]
	v_exp_f32_e32 v118, v118
	v_exp_f32_e32 v119, v119
	v_exp_f32_e32 v120, v120
	v_exp_f32_e32 v121, v121
	s_waitcnt lgkmcnt(10)
	v_mfma_f32_32x32x16_bf16 v[50:65], v[146:149], v[86:89], v[50:65]
	v_exp_f32_e32 v122, v122
	v_exp_f32_e32 v123, v123
	v_exp_f32_e32 v124, v124
	v_exp_f32_e32 v125, v125
	s_waitcnt lgkmcnt(8)
	v_mfma_f32_32x32x16_bf16 v[34:49], v[146:149], v[90:93], v[34:49]
	v_exp_f32_e32 v126, v126
	v_exp_f32_e32 v127, v127
	v_exp_f32_e32 v128, v128
	v_exp_f32_e32 v129, v129
	v_add_u32_e32 v98, s41, v245
	ds_read_b64_tr_b16 v[82:83],v98 offset:0
	ds_read_b64_tr_b16 v[84:85],v98 offset:512
	ds_read_b64_tr_b16 v[86:87],v98 offset:1024
	ds_read_b64_tr_b16 v[88:89],v98 offset:1536
	ds_read_b64_tr_b16 v[90:91],v98 offset:2048
	ds_read_b64_tr_b16 v[92:93],v98 offset:2560
	ds_read_b64_tr_b16 v[94:95],v98 offset:3072
	ds_read_b64_tr_b16 v[96:97],v98 offset:3584
	s_waitcnt lgkmcnt(0)
	s_nop 0
	v_mfma_f32_32x32x16_bf16 v[18:33], v[158:161], v[82:85], v[18:33]
	ds_read_b64_tr_b16 v[82:83],v98 offset:4096
	ds_read_b64_tr_b16 v[84:85],v98 offset:4608
	v_mfma_f32_32x32x16_bf16 v[18:33], v[154:157], v[86:89], v[18:33]
	ds_read_b64_tr_b16 v[86:87],v98 offset:5120
	ds_read_b64_tr_b16 v[88:89],v98 offset:5632
	v_mfma_f32_32x32x16_bf16 v[18:33], v[150:153], v[90:93], v[18:33]
	ds_read_b64_tr_b16 v[90:91],v98 offset:6144
	ds_read_b64_tr_b16 v[92:93],v98 offset:6656
	v_mfma_f32_32x32x16_bf16 v[18:33], v[146:149], v[94:97], v[18:33]
	ds_read_b64_tr_b16 v[94:95],v98 offset:7168
	ds_read_b64_tr_b16 v[96:97],v98 offset:7680
	s_waitcnt lgkmcnt(0)
	v_mfma_f32_32x32x16_bf16 v[2:17], v[158:161], v[82:85], v[2:17]
	s_mov_b64 s[4:5], -1
	s_and_b64 vcc, exec, s[66:67]
	v_mfma_f32_32x32x16_bf16 v[2:17], v[154:157], v[86:89], v[2:17]
	v_mfma_f32_32x32x16_bf16 v[2:17], v[150:153], v[90:93], v[2:17]
	v_mfma_f32_32x32x16_bf16 v[2:17], v[146:149], v[94:97], v[2:17]
	s_cbranch_vccz .LBB0_1036
	s_add_i32 s4, s47, -2
	s_cmp_ge_u32 s4, s46
	s_mov_b64 s[4:5], -1
	s_cbranch_scc0 .LBB0_1006
	s_waitcnt vmcnt(0) lgkmcnt(0)
	s_barrier
	s_mov_b64 s[4:5], 0

.LBB0_1018:
	s_waitcnt lgkmcnt(14)
	v_mfma_f32_32x32x16_bf16 v[50:65], v[158:161], v[218:221], v[50:65]
	v_exp_f32_e32 v98, v98
	v_exp_f32_e32 v99, v99
	v_exp_f32_e32 v100, v100
	v_exp_f32_e32 v101, v101
	s_waitcnt lgkmcnt(12)
	v_mfma_f32_32x32x16_bf16 v[34:49], v[158:161], v[214:217], v[34:49]
	v_exp_f32_e32 v102, v102
	v_exp_f32_e32 v103, v103
	v_exp_f32_e32 v104, v104
	v_exp_f32_e32 v105, v105
	v_cndmask_b32_e64 v122, 0, 1, s[76:77]
	v_cmp_ne_u32_e64 s[4:5], 1, v122
	s_andn2_b64 vcc, exec, s[76:77]
	v_add_u32_e32 v122, s40, v241
	s_cbranch_vccnz .LBB0_1020
	ds_read_b128 v[206:209], v122
	ds_read_b128 v[202:205], v122 offset:4096
.LBB0_1020:
	s_waitcnt lgkmcnt(10)
	v_mfma_f32_32x32x16_bf16 v[50:65], v[154:157], v[210:213], v[50:65]
	v_exp_f32_e32 v106, v106
	v_exp_f32_e32 v107, v107
	v_exp_f32_e32 v108, v108
	v_exp_f32_e32 v109, v109
	s_and_b64 vcc, exec, s[4:5]
	s_cbranch_vccnz .LBB0_1022
	v_xor_b32_e32 v122, 32, v122
	ds_read_b128 v[198:201], v122
	ds_read_b128 v[194:197], v122 offset:4096
.LBB0_1022:
	s_waitcnt lgkmcnt(8)
	v_mfma_f32_32x32x16_bf16 v[34:49], v[154:157], v[138:141], v[34:49]
	v_exp_f32_e32 v110, v110
	v_exp_f32_e32 v111, v111
	v_exp_f32_e32 v112, v112
	v_exp_f32_e32 v113, v113
	s_and_b64 vcc, exec, s[4:5]
	s_cbranch_vccnz .LBB0_1024
	v_xor_b32_e32 v122, 0x60, v122
	ds_read_b128 v[190:193], v122
	ds_read_b128 v[186:189], v122 offset:4096
.LBB0_1024:
	s_waitcnt lgkmcnt(6)
	v_mfma_f32_32x32x16_bf16 v[50:65], v[150:153], v[134:137], v[50:65]
	v_exp_f32_e32 v82, v82
	v_exp_f32_e32 v83, v83
	v_exp_f32_e32 v84, v84
	v_exp_f32_e32 v85, v85
	s_and_b64 vcc, exec, s[4:5]
	s_cbranch_vccnz .LBB0_1026
	v_xor_b32_e32 v122, 32, v122
	ds_read_b128 v[182:185], v122
	ds_read_b128 v[178:181], v122 offset:4096

.LBB0_1075:
	s_sub_i32 s2, 1, s78
	s_and_b64 s[0:1], s[6:7], exec
	s_cselect_b32 s0, s2, s78
	s_cmp_eq_u32 s0, 0
	s_cselect_b32 s1, s12, s13
	s_cmp_lt_i32 s0, 2
	s_cselect_b32 s79, s14, s79
	s_cselect_b32 s82, s1, s82
	s_ashr_i32 s0, s79, 31
	s_lshr_b32 s0, s0, 29
	s_add_i32 s0, s79, s0
	s_ashr_i32 s4, s0, 3
	v_mov_b32_e32 v52, v0
	s_and_b32 s0, s0, -8
	s_ashr_i32 s5, s4, 31
	v_readfirstlane_b32 s41, v52
	s_lshl_b32 s3, s82, 8
	s_sub_i32 s38, s79, s0
	s_ashr_i32 s33, s41, 6
	s_lshl_b64 s[0:1], s[4:5], 13
	s_ashr_i32 s2, s3, 31
	s_add_u32 s0, s0, s3
	s_addc_u32 s1, s1, s2
	s_lshl_b32 s8, s33, 5
	s_ashr_i32 s2, s8, 31
	s_add_u32 s28, s0, s8
	s_addc_u32 s29, s1, s2
	s_lshl_b64 s[0:1], s[28:29], 10
	v_readlane_b32 s16, v254, 56
	v_readlane_b32 s17, v254, 57
	s_add_u32 s0, s16, s0
	s_addc_u32 s1, s17, s1
	s_lshl_b32 s16, s38, 6
	s_ashr_i32 s17, s16, 31
	s_lshl_b64 s[30:31], s[16:17], 1
	s_add_u32 s0, s0, s30
	s_addc_u32 s1, s1, s31
	s_lshl_b64 s[4:5], s[4:5], 23
	v_readlane_b32 s34, v254, 58
	v_readlane_b32 s35, v254, 59
	s_add_u32 s2, s34, s4
	s_addc_u32 s17, s35, s5
	s_add_u32 s30, s2, s30
	s_addc_u32 s31, s17, s31
	v_readlane_b32 s34, v254, 60
	v_readlane_b32 s35, v254, 61
	s_add_u32 s2, s34, s4
	s_addc_u32 s35, s35, s5
	s_and_b32 s16, s16, 0xffffff80
	s_ashr_i32 s17, s16, 31
	v_and_b32_e32 v223, 63, v52
	s_lshl_b64 s[16:17], s[16:17], 1
	s_add_u32 s34, s2, s16
	v_lshrrev_b32_e32 v226, 3, v223
	v_lshl_add_u32 v226, s33, 3, v226
	v_lshrrev_b32_e32 v227, 4, v223
	v_mov_b32_e32 v224, s33
	v_and_b32_e32 v224, 1, v224
	v_lshl_add_u32 v227, v224, 2, v227
	v_and_b32_e32 v224, 7, v223
	v_xor_b32_e32 v227, v227, v224
	v_lshlrev_b32_e32 v227, 4, v227
	v_lshl_or_b32 v224, v226, 10, v227
	s_addc_u32 s35, s35, s17
	v_lshl_add_u64 v[2:3], s[30:31], 0, v[224:225]
	s_mov_b32 s30, 0
	s_ashr_i32 s31, s30, 31
	s_lshl_b32 s2, s33, 4
	v_bfe_u32 v221, v52, 2, 4
	v_lshl_add_u64 v[226:227], s[30:31], 1, v[2:3]
	v_and_or_b32 v2, s2, 48, v221
	s_ashr_i32 s2, s41, 3
	s_and_b32 s30, s2, 0xffffffe0
	s_ashr_i32 s31, s30, 31
	s_lshl_b32 s2, s33, 10
	v_lshlrev_b32_e32 v224, 10, v2
	v_lshlrev_b32_e32 v235, 3, v52
	s_cmp_lg_u32 0, -1
	v_lshl_add_u64 v[2:3], s[34:35], 0, v[224:225]
	v_and_b32_e32 v53, 24, v235
	s_cselect_b32 s34, 0, 0
	v_lshl_add_u64 v[2:3], s[30:31], 1, v[2:3]
	v_lshlrev_b32_e32 v224, 1, v53
	s_add_i32 s44, s2, s34
	s_mov_b32 s34, m0
	s_mov_b32 m0, s44
	s_nop 0
	global_load_lds_dwordx4 v[226:227], off
	s_mov_b32 m0, s34
	v_lshl_add_u64 v[50:51], v[2:3], 0, v[224:225]
	s_add_i32 s45, s44, 0x6000
	s_mov_b32 s34, m0
	s_mov_b32 m0, s45
	s_nop 0
	global_load_lds_dwordx4 v[50:51], off
	s_mov_b32 m0, s34
	s_mov_b64 s[34:35], 0x80
	v_lshl_add_u64 v[2:3], v[50:51], 0, s[34:35]
	v_and_b32_e32 v234, 31, v52
	s_add_i32 s34, s44, 0x8000
	s_mov_b32 s35, m0
	s_mov_b32 m0, s34
	s_nop 0
	global_load_lds_dwordx4 v[2:3], off
	s_mov_b32 m0, s35
	v_lshl_add_u64 v[2:3], v[226:227], 0, s[10:11]
	v_bfe_u32 v220, v52, 5, 1
	s_add_i32 s34, s44, 0x2000
	s_mov_b32 s35, m0
	s_mov_b32 m0, s34
	s_nop 0
	global_load_lds_dwordx4 v[2:3], off
	s_mov_b32 m0, s35
	v_lshlrev_b32_e32 v2, 10, v234
	v_lshl_or_b32 v3, v220, 4, v2
	global_load_dwordx4 v[174:177], v3, s[0:1]
	global_load_dwordx4 v[170:173], v3, s[0:1] offset:32
	global_load_dwordx4 v[150:153], v3, s[0:1] offset:64
	global_load_dwordx4 v[146:149], v3, s[0:1] offset:96
	v_mov_b32_e32 v2, 0
	v_mov_b32_e32 v18, v225
	v_lshlrev_b32_e32 v4, 7, v234
	v_bfe_u32 v5, v234, 1, 3
	v_xor_b32_e32 v5, v5, v220
	v_lshl_or_b32 v241, v5, 4, v4
	v_lshl_add_u64 v[4:5], v[226:227], 0, s[18:19]
	s_add_i32 s34, s44, 0x4000
	s_mov_b32 s0, m0
	s_mov_b32 m0, s34
	s_nop 0
	global_load_lds_dwordx4 v[4:5], off
	s_mov_b32 m0, s0
	s_waitcnt vmcnt(3) lgkmcnt(0)
	s_barrier
	ds_read_b128 v[4:7], v241
	v_mov_b32_e32 v19, v18
	v_mov_b32_e32 v20, v18
	v_mov_b32_e32 v21, v18
	v_mov_b32_e32 v22, v18
	v_mov_b32_e32 v23, v18
	v_mov_b32_e32 v24, v18
	v_mov_b32_e32 v25, v18
	v_mov_b32_e32 v26, v18
	v_mov_b32_e32 v27, v18
	v_mov_b32_e32 v28, v18
	v_mov_b32_e32 v29, v18
	v_mov_b32_e32 v30, v18
	v_mov_b32_e32 v31, v18
	v_mov_b32_e32 v32, v18
	v_mov_b32_e32 v33, v18
	s_add_i32 s0, s3, 0x100
	s_ashr_i32 s46, s0, 6
	v_or_b32_e32 v239, s8, v234
	s_cmp_gt_i32 s46, 4
	v_lshlrev_b32_e32 v236, 2, v220
	s_waitcnt vmcnt(3) lgkmcnt(0)
	v_mfma_f32_32x32x16_bf16 v[34:49], v[4:7], v[174:177], v[18:33]
	ds_read_b128 v[4:7], v241 offset:4096
	s_waitcnt lgkmcnt(0)
	v_mfma_f32_32x32x16_bf16 v[18:33], v[4:7], v[174:177], v[18:33]
	v_xor_b32_e32 v241, 32, v241
	ds_read_b128 v[4:7], v241
	s_waitcnt vmcnt(2) lgkmcnt(0)
	v_mfma_f32_32x32x16_bf16 v[34:49], v[4:7], v[170:173], v[34:49]
	ds_read_b128 v[4:7], v241 offset:4096
	s_waitcnt lgkmcnt(0)
	v_mfma_f32_32x32x16_bf16 v[18:33], v[4:7], v[170:173], v[18:33]
	v_xor_b32_e32 v241, 0x60, v241
	ds_read_b128 v[4:7], v241
	s_waitcnt vmcnt(1) lgkmcnt(0)
	v_mfma_f32_32x32x16_bf16 v[34:49], v[4:7], v[150:153], v[34:49]
	ds_read_b128 v[4:7], v241 offset:4096
	s_waitcnt lgkmcnt(0)
	v_mfma_f32_32x32x16_bf16 v[18:33], v[4:7], v[150:153], v[18:33]
	v_xor_b32_e32 v241, 32, v241
	ds_read_b128 v[4:7], v241
	s_waitcnt vmcnt(0) lgkmcnt(0)
	v_mfma_f32_32x32x16_bf16 v[34:49], v[4:7], v[146:149], v[34:49]
	ds_read_b128 v[4:7], v241 offset:4096
	v_xor_b32_e32 v241, 0x60, v241
	s_waitcnt lgkmcnt(0)
	v_mfma_f32_32x32x16_bf16 v[18:33], v[4:7], v[146:149], v[18:33]
	s_nop 15
	s_nop 7
	s_cbranch_scc1 .LBB0_1077
	v_lshlrev_b32_e32 v3, 2, v220
	v_subrev_u32_e32 v3, s3, v3
	v_or_b32_e32 v4, 32, v3
	v_cmp_le_i32_e32 vcc, v4, v239
	v_or_b32_e32 v4, 33, v3
	s_nop 5
	v_cndmask_b32_e32 v18, v1, v18, vcc
	v_cmp_lt_i32_e32 vcc, v3, v239
	s_nop 1
	v_cndmask_b32_e32 v35, v1, v35, vcc
	v_cmp_le_i32_e32 vcc, v3, v239
	s_nop 1
	v_cndmask_b32_e32 v34, v1, v34, vcc
	v_cmp_le_i32_e32 vcc, v4, v239
	v_or_b32_e32 v4, 2, v3
	s_nop 0
	v_cndmask_b32_e32 v19, v1, v19, vcc
	v_cmp_le_i32_e32 vcc, v4, v239
	v_or_b32_e32 v4, 34, v3
	s_nop 0
	v_cndmask_b32_e32 v36, v1, v36, vcc
	v_cmp_le_i32_e32 vcc, v4, v239
	v_or_b32_e32 v4, 3, v3
	s_nop 0
	v_cndmask_b32_e32 v20, v1, v20, vcc
	v_cmp_le_i32_e32 vcc, v4, v239
	v_or_b32_e32 v4, 35, v3
	s_nop 0
	v_cndmask_b32_e32 v37, v1, v37, vcc
	v_cmp_le_i32_e32 vcc, v4, v239
	v_or_b32_e32 v4, 8, v3
	s_nop 0
	v_cndmask_b32_e32 v21, v1, v21, vcc
	v_cmp_le_i32_e32 vcc, v4, v239
	v_or_b32_e32 v4, 40, v3
	s_nop 0
	v_cndmask_b32_e32 v38, v1, v38, vcc
	v_cmp_le_i32_e32 vcc, v4, v239
	v_or_b32_e32 v4, 9, v3
	s_nop 0
	v_cndmask_b32_e32 v22, v1, v22, vcc
	v_cmp_le_i32_e32 vcc, v4, v239
	v_or_b32_e32 v4, 41, v3
	s_nop 0
	v_cndmask_b32_e32 v39, v1, v39, vcc
	v_cmp_le_i32_e32 vcc, v4, v239
	v_or_b32_e32 v4, 10, v3
	s_nop 0
	v_cndmask_b32_e32 v23, v1, v23, vcc
	v_cmp_le_i32_e32 vcc, v4, v239
	v_or_b32_e32 v4, 42, v3
	s_nop 0
	v_cndmask_b32_e32 v40, v1, v40, vcc
	v_cmp_le_i32_e32 vcc, v4, v239
	v_or_b32_e32 v4, 11, v3
	s_nop 0
	v_cndmask_b32_e32 v24, v1, v24, vcc
	v_cmp_le_i32_e32 vcc, v4, v239
	v_or_b32_e32 v4, 43, v3
	s_nop 0
	v_cndmask_b32_e32 v41, v1, v41, vcc
	v_cmp_le_i32_e32 vcc, v4, v239
	v_or_b32_e32 v4, 16, v3
	s_nop 0
	v_cndmask_b32_e32 v25, v1, v25, vcc
	v_cmp_le_i32_e32 vcc, v4, v239
	v_or_b32_e32 v4, 48, v3
	s_nop 0
	v_cndmask_b32_e32 v42, v1, v42, vcc
	v_cmp_le_i32_e32 vcc, v4, v239
	v_or_b32_e32 v4, 17, v3
	s_nop 0
	v_cndmask_b32_e32 v26, v1, v26, vcc
	v_cmp_le_i32_e32 vcc, v4, v239
	v_or_b32_e32 v4, 49, v3
	s_nop 0
	v_cndmask_b32_e32 v43, v1, v43, vcc
	v_cmp_le_i32_e32 vcc, v4, v239
	v_or_b32_e32 v4, 18, v3
	s_nop 0
	v_cndmask_b32_e32 v27, v1, v27, vcc
	v_cmp_le_i32_e32 vcc, v4, v239
	v_or_b32_e32 v4, 50, v3
	s_nop 0
	v_cndmask_b32_e32 v44, v1, v44, vcc
	v_cmp_le_i32_e32 vcc, v4, v239
	v_or_b32_e32 v4, 19, v3
	s_nop 0
	v_cndmask_b32_e32 v28, v1, v28, vcc
	v_cmp_le_i32_e32 vcc, v4, v239
	v_or_b32_e32 v4, 51, v3
	s_nop 0
	v_cndmask_b32_e32 v45, v1, v45, vcc
	v_cmp_le_i32_e32 vcc, v4, v239
	v_or_b32_e32 v4, 24, v3
	s_nop 0
	v_cndmask_b32_e32 v29, v1, v29, vcc
	v_cmp_le_i32_e32 vcc, v4, v239
	v_or_b32_e32 v4, 56, v3
	s_nop 0
	v_cndmask_b32_e32 v46, v1, v46, vcc
	v_cmp_le_i32_e32 vcc, v4, v239
	v_or_b32_e32 v4, 25, v3
	s_nop 0
	v_cndmask_b32_e32 v30, v1, v30, vcc
	v_cmp_le_i32_e32 vcc, v4, v239
	v_or_b32_e32 v4, 57, v3
	s_nop 0
	v_cndmask_b32_e32 v47, v1, v47, vcc
	v_cmp_le_i32_e32 vcc, v4, v239
	v_or_b32_e32 v4, 26, v3
	s_nop 0
	v_cndmask_b32_e32 v31, v1, v31, vcc
	v_cmp_le_i32_e32 vcc, v4, v239
	v_or_b32_e32 v4, 58, v3
	s_nop 0
	v_cndmask_b32_e32 v48, v1, v48, vcc
	v_cmp_le_i32_e32 vcc, v4, v239
	v_or_b32_e32 v4, 27, v3
	v_or_b32_e32 v3, 59, v3
	v_cndmask_b32_e32 v32, v1, v32, vcc
	v_cmp_le_i32_e32 vcc, v4, v239
	s_nop 1
	v_cndmask_b32_e32 v49, v1, v49, vcc
	v_cmp_le_i32_e32 vcc, v3, v239
	s_nop 1
	v_cndmask_b32_e32 v33, v1, v33, vcc
.LBB0_1077:
	s_and_b32 s1, s41, 0x3fffffc0
	s_cmp_lg_u32 0, -1
	v_lshlrev_b32_e32 v3, 1, v52
	s_cselect_b32 s0, 0, 0
	v_lshlrev_b32_e32 v4, 4, v52
	v_and_b32_e32 v3, 32, v3
	s_add_i32 s3, s0, 0x6000
	v_and_b32_e32 v4, 0xc0, v4
	v_add_u32_e32 v54, s3, v3
	v_lshl_or_b32 v55, v220, 8, v4
	v_add_u32_e32 v3, 0, v3
	v_add3_u32 v242, v3, v53, v55
	v_add3_u32 v237, v54, v53, v55
	v_max3_f32 v53, v34, v35, v18
	v_max3_f32 v54, v36, v37, v19
	s_lshl_b32 s1, s1, 2
	v_max3_f32 v53, v53, v20, v21
	v_max3_f32 v54, v54, v40, v41
	s_add_i32 s39, s1, 0
	v_max3_f32 v53, v53, v38, v39
	v_max3_f32 v54, v54, v24, v25
	s_add_i32 s2, s0, s2
	v_max3_f32 v53, v53, v22, v23
	v_max3_f32 v54, v54, v44, v45
	s_add_i32 s0, s2, 0xa000
	v_max3_f32 v53, v53, v42, v43
	v_max3_f32 v54, v54, v28, v29
	s_add_i32 s2, s2, 0xc000
	v_max3_f32 v53, v53, v26, v27
	v_max3_f32 v54, v54, v48, v49
	s_add_i32 s39, s39, 0x12000
	v_max3_f32 v53, v53, v46, v47
	v_max3_f32 v54, v54, v32, v33
	s_mov_b32 s8, 1
	v_max3_f32 v53, v53, v30, v31
	s_mov_b32 s43, 0
	v_max_f32_e32 v53, v53, v54
	v_mov_b32_e32 v3, v2
	v_mov_b32_e32 v54, v53
	s_nop 1
	v_permlane32_swap_b32_e32 v53, v54
	v_max_f32_e32 v53, v53, v54
	v_mov_b32_e32 v4, v2
	v_add_f32_e32 v240, v225, v53
	v_sub_f32_e32 v18, v18, v53
	v_sub_f32_e32 v19, v19, v53
	v_sub_f32_e32 v34, v34, v53
	v_sub_f32_e32 v35, v35, v53
	v_sub_f32_e32 v36, v36, v53
	s_nop 0
	v_xor_b32_e32 v66, 0x80000000, v240
	v_mov_b32_e32 v67, v66
	v_mov_b32_e32 v68, v66
	v_mov_b32_e32 v69, v66
	v_mov_b32_e32 v70, v66
	v_mov_b32_e32 v71, v66
	v_mov_b32_e32 v72, v66
	v_mov_b32_e32 v73, v66
	v_mov_b32_e32 v74, v66
	v_mov_b32_e32 v75, v66
	v_mov_b32_e32 v76, v66
	v_mov_b32_e32 v77, v66
	v_mov_b32_e32 v78, v66
	v_mov_b32_e32 v79, v66
	v_mov_b32_e32 v80, v66
	v_mov_b32_e32 v81, v66
	s_waitcnt vmcnt(0) lgkmcnt(0)
	s_barrier
	v_exp_f32_e32 v82, v18
	v_exp_f32_e32 v83, v19
	v_lshl_add_u64 v[18:19], v[226:227], 0, s[20:21]
	s_mov_b32 s1, m0
	s_mov_b32 m0, s44
	s_nop 0
	global_load_lds_dwordx4 v[18:19], off
	s_mov_b32 m0, s1
	v_lshl_add_u64 v[18:19], v[50:51], 0, s[10:11]
	s_mov_b32 s1, m0
	s_mov_b32 m0, s0
	s_nop 0
	global_load_lds_dwordx4 v[18:19], off
	s_mov_b32 m0, s1
	s_mov_b64 s[0:1], 0x10080
	v_lshl_add_u64 v[18:19], v[50:51], 0, s[0:1]
	s_mov_b32 s0, m0
	s_mov_b32 m0, s2
	s_nop 0
	global_load_lds_dwordx4 v[18:19], off
	s_mov_b32 m0, s0
	ds_read_b128 v[206:209], v241 offset:8192
	ds_read_b128 v[198:201], v241 offset:12288
	v_xor_b32_e32 v241, 32, v241
	ds_read_b128 v[202:205], v241 offset:8192
	ds_read_b128 v[194:197], v241 offset:12288
	v_xor_b32_e32 v241, 0x60, v241
	ds_read_b128 v[190:193], v241 offset:8192
	ds_read_b128 v[186:189], v241 offset:12288
	v_xor_b32_e32 v241, 32, v241
	ds_read_b128 v[182:185], v241 offset:8192
	ds_read_b128 v[178:181], v241 offset:12288
	v_xor_b32_e32 v241, 0x60, v241
	v_sub_f32_e32 v20, v20, v53
	v_sub_f32_e32 v37, v37, v53
	v_sub_f32_e32 v21, v21, v53
	v_sub_f32_e32 v38, v38, v53
	v_sub_f32_e32 v22, v22, v53
	v_sub_f32_e32 v39, v39, v53
	v_sub_f32_e32 v23, v23, v53
	v_sub_f32_e32 v40, v40, v53
	v_sub_f32_e32 v24, v24, v53
	v_sub_f32_e32 v41, v41, v53
	v_sub_f32_e32 v25, v25, v53
	v_sub_f32_e32 v42, v42, v53
	v_sub_f32_e32 v26, v26, v53
	v_sub_f32_e32 v43, v43, v53
	v_sub_f32_e32 v27, v27, v53
	v_sub_f32_e32 v44, v44, v53
	v_sub_f32_e32 v28, v28, v53
	v_sub_f32_e32 v45, v45, v53
	v_sub_f32_e32 v29, v29, v53
	v_sub_f32_e32 v46, v46, v53
	v_sub_f32_e32 v30, v30, v53
	v_sub_f32_e32 v47, v47, v53
	v_sub_f32_e32 v31, v31, v53
	v_sub_f32_e32 v48, v48, v53
	v_sub_f32_e32 v32, v32, v53
	v_sub_f32_e32 v49, v49, v53
	v_sub_f32_e32 v33, v33, v53
	v_exp_f32_e32 v98, v34
	v_exp_f32_e32 v99, v35
	v_exp_f32_e32 v100, v36
	v_exp_f32_e32 v101, v37
	v_exp_f32_e32 v102, v38
	v_exp_f32_e32 v103, v39
	v_exp_f32_e32 v104, v40
	v_exp_f32_e32 v105, v41
	v_exp_f32_e32 v106, v42
	v_exp_f32_e32 v107, v43
	v_exp_f32_e32 v108, v44
	v_exp_f32_e32 v109, v45
	v_exp_f32_e32 v110, v46
	v_exp_f32_e32 v111, v47
	v_exp_f32_e32 v112, v48
	v_exp_f32_e32 v113, v49
	v_exp_f32_e32 v84, v20
	v_exp_f32_e32 v85, v21
	v_exp_f32_e32 v86, v22
	v_exp_f32_e32 v87, v23
	v_exp_f32_e32 v88, v24
	v_exp_f32_e32 v89, v25
	v_exp_f32_e32 v90, v26
	v_exp_f32_e32 v91, v27
	v_exp_f32_e32 v92, v28
	v_exp_f32_e32 v93, v29
	v_exp_f32_e32 v94, v30
	v_exp_f32_e32 v95, v31
	v_exp_f32_e32 v96, v32
	v_exp_f32_e32 v97, v33
	s_waitcnt vmcnt(3) lgkmcnt(0)
	s_barrier
	v_and_b32_e32 v18, 3, v52
	v_mov_b32_e32 v5, v2
	v_mov_b32_e32 v6, v2
	v_mov_b32_e32 v7, v2
	v_mov_b32_e32 v8, v2
	v_mov_b32_e32 v9, v2
	v_mov_b32_e32 v10, v2
	v_mov_b32_e32 v11, v2
	v_mov_b32_e32 v12, v2
	v_mov_b32_e32 v13, v2
	v_mov_b32_e32 v14, v2
	v_mov_b32_e32 v15, v2
	v_mov_b32_e32 v16, v2
	v_mov_b32_e32 v17, v2
	s_cmp_lt_i32 s46, 7
	v_cmp_gt_u32_e64 s[0:1], 32, v223
	v_lshlrev_b32_e32 v243, 4, v220
	v_lshl_add_u32 v238, v234, 2, s39
	v_lshlrev_b32_e32 v224, 4, v18
	s_cbranch_scc1 .LBB0_1093
	s_add_i32 s42, s46, -5
	s_lshl_b64 s[2:3], s[30:31], 1
	s_add_u32 s2, s2, s16
	s_addc_u32 s3, s3, s17
	s_add_u32 s2, s2, s4
	s_addc_u32 s3, s3, s5
	v_lshl_add_u64 v[18:19], s[2:3], 0, v[224:225]
	s_lshl_b32 s2, s41, 8
	s_and_b32 s2, s2, 0xc000
	v_lshl_or_b32 v20, v221, 10, s2
	v_mov_b32_e32 v21, v225
	v_readlane_b32 s52, v254, 6
	v_lshl_add_u64 v[18:19], v[18:19], 0, v[20:21]
	v_readlane_b32 s58, v254, 12
	v_readlane_b32 s59, v254, 13
	v_mov_b64_e32 v[64:65], v[16:17]
	v_mov_b64_e32 v[48:49], v[16:17]
	v_lshl_add_u64 v[214:215], s[58:59], 0, v[18:19]
	v_mov_b64_e32 v[32:33], v[16:17]
	s_movk_i32 s48, 0x2000
	v_add_u32_e32 v228, 0x2000, v237
	s_movk_i32 s43, 0x4000
	s_mov_b32 s2, 0
	v_mov_b32_e32 v244, 0
	s_mov_b64 s[34:35], 0
	v_mov_b64_e32 v[62:63], v[14:15]
	v_mov_b64_e32 v[60:61], v[12:13]
	v_mov_b64_e32 v[58:59], v[10:11]
	v_mov_b64_e32 v[56:57], v[8:9]
	v_mov_b64_e32 v[54:55], v[6:7]
	v_mov_b64_e32 v[52:53], v[4:5]
	v_mov_b64_e32 v[50:51], v[2:3]
	v_mov_b64_e32 v[46:47], v[14:15]
	v_mov_b64_e32 v[44:45], v[12:13]
	v_mov_b64_e32 v[42:43], v[10:11]
	v_mov_b64_e32 v[40:41], v[8:9]
	v_mov_b64_e32 v[38:39], v[6:7]
	v_mov_b64_e32 v[36:37], v[4:5]
	v_mov_b64_e32 v[34:35], v[2:3]
	v_mov_b64_e32 v[30:31], v[14:15]
	v_mov_b64_e32 v[28:29], v[12:13]
	v_mov_b64_e32 v[26:27], v[10:11]
	v_mov_b64_e32 v[24:25], v[8:9]
	v_mov_b64_e32 v[22:23], v[6:7]
	v_mov_b64_e32 v[20:21], v[4:5]
	v_mov_b64_e32 v[18:19], v[2:3]
	v_readlane_b32 s53, v254, 7
	v_readlane_b32 s54, v254, 8
	v_readlane_b32 s55, v254, 9
	v_readlane_b32 s56, v254, 10
	v_readlane_b32 s57, v254, 11
	v_readfirstlane_b32 s98, v226
	v_readfirstlane_b32 s99, v227
	v_readfirstlane_b32 s100, v214
	v_readfirstlane_b32 s101, v215
	s_sub_u32 s98, s98, 64
	s_subb_u32 s99, s99, 0
	s_mov_b32 s3, 0
	v_subrev_u32_e32 v218, s98, v226
	v_subrev_u32_e32 v219, s100, v214
	s_add_u32 s98, s98, s34
	s_addc_u32 s99, s99, s35
	s_add_u32 s98, s98, s22
	s_addc_u32 s99, s99, s23
	s_add_u32 s100, s100, s34
	s_addc_u32 s101, s101, s35
	s_add_u32 s100, s100, s24
	s_addc_u32 s101, s101, s25

.LBB0_1080:
	ds_read_b128 v[82:85], v94
	ds_read_b128 v[198:201], v94 offset:4096
	v_xor_b32_e32 v94, 32, v94
	ds_read_b128 v[202:205], v94
	ds_read_b128 v[194:197], v94 offset:4096
	s_waitcnt lgkmcnt(4)
	v_mfma_f32_32x32x16_bf16 v[50:65], v[158:161], v[106:109], v[50:65]
	v_exp_f32_e32 v130, v130
	v_exp_f32_e32 v131, v131
	v_exp_f32_e32 v132, v132
	v_xor_b32_e32 v94, 0x60, v94
	ds_read_b128 v[190:193], v94
	ds_read_b128 v[186:189], v94 offset:4096
	v_xor_b32_e32 v94, 32, v94
	ds_read_b128 v[182:185], v94
	ds_read_b128 v[178:181], v94 offset:4096
	ds_read_b64_tr_b16 v[98:99],v102 offset:3072
	ds_read_b64_tr_b16 v[100:101],v102 offset:3584
	ds_read_b64_tr_b16 v[94:95],v102 offset:2048
	ds_read_b64_tr_b16 v[96:97],v102 offset:2560
	v_mfma_f32_32x32x16_bf16 v[34:49], v[158:161], v[110:113], v[34:49]
	v_exp_f32_e32 v133, v133
	v_exp_f32_e32 v134, v134
	v_exp_f32_e32 v135, v135
	v_mfma_f32_32x32x16_bf16 v[50:65], v[154:157], v[86:89], v[50:65]
	v_exp_f32_e32 v136, v136
	v_exp_f32_e32 v137, v137
	v_exp_f32_e32 v138, v138
	ds_read_b64_tr_b16 v[86:87],v102 offset:0
	ds_read_b64_tr_b16 v[88:89],v102 offset:512
	v_mfma_f32_32x32x16_bf16 v[34:49], v[154:157], v[90:93], v[34:49]
	v_exp_f32_e32 v139, v139
	v_exp_f32_e32 v140, v140
	v_exp_f32_e32 v141, v141
	ds_read_b64_tr_b16 v[90:91],v102 offset:1024
	ds_read_b64_tr_b16 v[92:93],v102 offset:1536
	s_waitcnt lgkmcnt(6)
	v_mfma_f32_32x32x16_bf16 v[18:33], v[154:157], v[98:101], v[18:33]
	v_exp_f32_e32 v142, v142
	v_exp_f32_e32 v143, v143
	v_exp_f32_e32 v144, v144
	ds_read_b64_tr_b16 v[98:99],v102 offset:7168
	ds_read_b64_tr_b16 v[100:101],v102 offset:7680
	s_waitcnt lgkmcnt(6)
	v_mfma_f32_32x32x16_bf16 v[18:33], v[158:161], v[94:97], v[18:33]
	v_exp_f32_e32 v145, v145
	v_exp_f32_e32 v114, v114
	v_exp_f32_e32 v115, v115
	ds_read_b64_tr_b16 v[94:95],v102 offset:6144
	ds_read_b64_tr_b16 v[96:97],v102 offset:6656
	s_waitcnt lgkmcnt(6)
	v_mfma_f32_32x32x16_bf16 v[18:33], v[166:169], v[86:89], v[18:33]
	v_exp_f32_e32 v116, v116
	v_exp_f32_e32 v117, v117
	v_exp_f32_e32 v118, v118
	ds_read_b64_tr_b16 v[86:87],v102 offset:4096
	ds_read_b64_tr_b16 v[88:89],v102 offset:4608
	s_waitcnt lgkmcnt(6)
	v_mfma_f32_32x32x16_bf16 v[18:33], v[162:165], v[90:93], v[18:33]
	v_exp_f32_e32 v119, v119
	v_exp_f32_e32 v120, v120
	v_exp_f32_e32 v121, v121
	ds_read_b64_tr_b16 v[90:91],v102 offset:5120
	ds_read_b64_tr_b16 v[92:93],v102 offset:5632
	s_waitcnt lgkmcnt(6)
	v_mfma_f32_32x32x16_bf16 v[2:17], v[154:157], v[98:101], v[2:17]
	v_exp_f32_e32 v122, v122
	v_exp_f32_e32 v123, v123
	s_waitcnt vmcnt(3) lgkmcnt(0)
	s_barrier
	v_mfma_f32_32x32x16_bf16 v[2:17], v[158:161], v[94:97], v[2:17]
	v_exp_f32_e32 v124, v124
	v_exp_f32_e32 v125, v125
	v_mfma_f32_32x32x16_bf16 v[2:17], v[166:169], v[86:89], v[2:17]
	v_exp_f32_e32 v126, v126
	v_exp_f32_e32 v127, v127
	v_mfma_f32_32x32x16_bf16 v[2:17], v[162:165], v[90:93], v[2:17]
	v_exp_f32_e32 v128, v128
	v_exp_f32_e32 v129, v129
	s_cmp_eq_u32 s3, 0
	s_cbranch_scc1 .LBB0_1082
	s_waitcnt lgkmcnt(0)
	s_mov_b32 s3, 0
	v_add_u32_e32 v229, s39, v243
	ds_read_b128 v[86:89], v229 offset:96
	ds_read_b128 v[90:93], v229 offset:64
	ds_read_b128 v[94:97], v229 offset:32
	ds_read_b128 v[98:101], v229
	s_waitcnt lgkmcnt(3)
	v_pk_mul_f32 v[62:63], v[62:63], v[86:87]
	s_waitcnt lgkmcnt(2)
	v_pk_mul_f32 v[58:59], v[58:59], v[90:91]
	s_waitcnt lgkmcnt(1)
	v_pk_mul_f32 v[54:55], v[54:55], v[94:95]
	v_pk_mul_f32 v[64:65], v[64:65], v[88:89]
	v_pk_mul_f32 v[60:61], v[60:61], v[92:93]
	v_pk_mul_f32 v[56:57], v[56:57], v[96:97]
	s_waitcnt lgkmcnt(0)
	v_pk_mul_f32 v[52:53], v[52:53], v[100:101]
	v_pk_mul_f32 v[50:51], v[50:51], v[98:99]
	v_pk_mul_f32 v[46:47], v[46:47], v[86:87]
	v_pk_mul_f32 v[42:43], v[42:43], v[90:91]
	v_pk_mul_f32 v[38:39], v[38:39], v[94:95]
	v_pk_mul_f32 v[48:49], v[48:49], v[88:89]
	v_pk_mul_f32 v[44:45], v[44:45], v[92:93]
	v_pk_mul_f32 v[40:41], v[40:41], v[96:97]
	v_pk_mul_f32 v[36:37], v[36:37], v[100:101]
	v_pk_mul_f32 v[34:35], v[34:35], v[98:99]
	v_pk_mul_f32 v[30:31], v[30:31], v[86:87]
	v_pk_mul_f32 v[26:27], v[26:27], v[90:91]
	v_pk_mul_f32 v[22:23], v[22:23], v[94:95]
	v_pk_mul_f32 v[32:33], v[32:33], v[88:89]
	v_pk_mul_f32 v[28:29], v[28:29], v[92:93]
	v_pk_mul_f32 v[24:25], v[24:25], v[96:97]
	v_pk_mul_f32 v[20:21], v[20:21], v[100:101]
	v_pk_mul_f32 v[18:19], v[18:19], v[98:99]
	v_pk_mul_f32 v[14:15], v[14:15], v[86:87]
	v_pk_mul_f32 v[10:11], v[10:11], v[90:91]
	v_pk_mul_f32 v[6:7], v[6:7], v[94:95]
	v_pk_mul_f32 v[16:17], v[16:17], v[88:89]
	v_pk_mul_f32 v[12:13], v[12:13], v[92:93]
	v_pk_mul_f32 v[8:9], v[8:9], v[96:97]
	v_pk_mul_f32 v[4:5], v[4:5], v[100:101]
	v_pk_mul_f32 v[2:3], v[2:3], v[98:99]

.LBB0_1083:
	v_add_u32_e32 v126, s40, v241
	ds_read_b128 v[206:209], v126
	ds_read_b128 v[198:201], v126 offset:4096
	v_xor_b32_e32 v126, 32, v126
	ds_read_b128 v[202:205], v126
	ds_read_b128 v[194:197], v126 offset:4096
	s_waitcnt lgkmcnt(4)
	v_mfma_f32_32x32x16_bf16 v[50:65], v[158:161], v[138:141], v[50:65]
	v_exp_f32_e32 v98, v98
	v_exp_f32_e32 v99, v99
	v_exp_f32_e32 v100, v100
	v_xor_b32_e32 v126, 0x60, v126
	ds_read_b128 v[190:193], v126
	ds_read_b128 v[186:189], v126 offset:4096
	v_xor_b32_e32 v126, 32, v126
	ds_read_b128 v[182:185], v126
	ds_read_b128 v[178:181], v126 offset:4096
	ds_read_b64_tr_b16 v[126:127],v130 offset:3072
	ds_read_b64_tr_b16 v[128:129],v130 offset:3584
	v_mfma_f32_32x32x16_bf16 v[34:49], v[158:161], v[114:117], v[34:49]
	v_exp_f32_e32 v101, v101
	v_exp_f32_e32 v102, v102
	v_exp_f32_e32 v103, v103
	ds_read_b64_tr_b16 v[114:115],v130 offset:0
	ds_read_b64_tr_b16 v[116:117],v130 offset:512
	v_mfma_f32_32x32x16_bf16 v[50:65], v[154:157], v[118:121], v[50:65]
	v_exp_f32_e32 v104, v104
	v_exp_f32_e32 v105, v105
	v_exp_f32_e32 v106, v106
	ds_read_b64_tr_b16 v[118:119],v130 offset:1024
	ds_read_b64_tr_b16 v[120:121],v130 offset:1536
	v_mfma_f32_32x32x16_bf16 v[34:49], v[154:157], v[122:125], v[34:49]
	v_exp_f32_e32 v107, v107
	v_exp_f32_e32 v108, v108
	v_exp_f32_e32 v109, v109
	ds_read_b64_tr_b16 v[122:123],v130 offset:2048
	ds_read_b64_tr_b16 v[124:125],v130 offset:2560
	s_waitcnt lgkmcnt(6)
	v_mfma_f32_32x32x16_bf16 v[18:33], v[154:157], v[126:129], v[18:33]
	v_exp_f32_e32 v110, v110
	v_exp_f32_e32 v111, v111
	v_exp_f32_e32 v112, v112
	ds_read_b64_tr_b16 v[126:127],v130 offset:7168
	ds_read_b64_tr_b16 v[128:129],v130 offset:7680
	s_waitcnt lgkmcnt(6)
	v_mfma_f32_32x32x16_bf16 v[18:33], v[166:169], v[114:117], v[18:33]
	v_exp_f32_e32 v113, v113
	v_exp_f32_e32 v82, v82
	v_exp_f32_e32 v83, v83
	ds_read_b64_tr_b16 v[114:115],v130 offset:4096
	ds_read_b64_tr_b16 v[116:117],v130 offset:4608
	s_waitcnt lgkmcnt(6)
	v_mfma_f32_32x32x16_bf16 v[18:33], v[162:165], v[118:121], v[18:33]
	v_exp_f32_e32 v84, v84
	v_exp_f32_e32 v85, v85
	v_exp_f32_e32 v86, v86
	ds_read_b64_tr_b16 v[118:119],v130 offset:5120
	ds_read_b64_tr_b16 v[120:121],v130 offset:5632
	s_waitcnt lgkmcnt(6)
	v_mfma_f32_32x32x16_bf16 v[18:33], v[158:161], v[122:125], v[18:33]
	v_exp_f32_e32 v87, v87
	v_exp_f32_e32 v88, v88
	v_exp_f32_e32 v89, v89
	ds_read_b64_tr_b16 v[122:123],v130 offset:6144
	ds_read_b64_tr_b16 v[124:125],v130 offset:6656
	s_waitcnt lgkmcnt(6)
	v_mfma_f32_32x32x16_bf16 v[2:17], v[154:157], v[126:129], v[2:17]
	v_exp_f32_e32 v90, v90
	v_exp_f32_e32 v91, v91
	s_waitcnt vmcnt(3) lgkmcnt(0)
	s_barrier
	v_mfma_f32_32x32x16_bf16 v[2:17], v[166:169], v[114:117], v[2:17]
	v_exp_f32_e32 v92, v92
	v_exp_f32_e32 v93, v93
	v_mfma_f32_32x32x16_bf16 v[2:17], v[162:165], v[118:121], v[2:17]
	v_exp_f32_e32 v94, v94
	v_exp_f32_e32 v95, v95
	v_mfma_f32_32x32x16_bf16 v[2:17], v[158:161], v[122:125], v[2:17]
	v_exp_f32_e32 v96, v96
	v_exp_f32_e32 v97, v97
	s_cmp_eq_u32 s3, 0
	s_cbranch_scc1 .LBB0_1085
	s_waitcnt lgkmcnt(0)
	s_mov_b32 s3, 0
	v_add_u32_e32 v229, s39, v243
	ds_read_b128 v[114:117], v229 offset:96
	ds_read_b128 v[118:121], v229 offset:64
	ds_read_b128 v[122:125], v229 offset:32
	ds_read_b128 v[126:129], v229
	s_waitcnt lgkmcnt(3)
	v_pk_mul_f32 v[62:63], v[62:63], v[114:115]
	s_waitcnt lgkmcnt(2)
	v_pk_mul_f32 v[58:59], v[58:59], v[118:119]
	s_waitcnt lgkmcnt(1)
	v_pk_mul_f32 v[54:55], v[54:55], v[122:123]
	v_pk_mul_f32 v[64:65], v[64:65], v[116:117]
	v_pk_mul_f32 v[60:61], v[60:61], v[120:121]
	v_pk_mul_f32 v[56:57], v[56:57], v[124:125]
	s_waitcnt lgkmcnt(0)
	v_pk_mul_f32 v[52:53], v[52:53], v[128:129]
	v_pk_mul_f32 v[50:51], v[50:51], v[126:127]
	v_pk_mul_f32 v[46:47], v[46:47], v[114:115]
	v_pk_mul_f32 v[42:43], v[42:43], v[118:119]
	v_pk_mul_f32 v[38:39], v[38:39], v[122:123]
	v_pk_mul_f32 v[48:49], v[48:49], v[116:117]
	v_pk_mul_f32 v[44:45], v[44:45], v[120:121]
	v_pk_mul_f32 v[40:41], v[40:41], v[124:125]
	v_pk_mul_f32 v[36:37], v[36:37], v[128:129]
	v_pk_mul_f32 v[34:35], v[34:35], v[126:127]
	v_pk_mul_f32 v[30:31], v[30:31], v[114:115]
	v_pk_mul_f32 v[26:27], v[26:27], v[118:119]
	v_pk_mul_f32 v[22:23], v[22:23], v[122:123]
	v_pk_mul_f32 v[32:33], v[32:33], v[116:117]
	v_pk_mul_f32 v[28:29], v[28:29], v[120:121]
	v_pk_mul_f32 v[24:25], v[24:25], v[124:125]
	v_pk_mul_f32 v[20:21], v[20:21], v[128:129]
	v_pk_mul_f32 v[18:19], v[18:19], v[126:127]
	v_pk_mul_f32 v[14:15], v[14:15], v[114:115]
	v_pk_mul_f32 v[10:11], v[10:11], v[118:119]
	v_pk_mul_f32 v[6:7], v[6:7], v[122:123]
	v_pk_mul_f32 v[16:17], v[16:17], v[116:117]
	v_pk_mul_f32 v[12:13], v[12:13], v[120:121]
	v_pk_mul_f32 v[8:9], v[8:9], v[124:125]
	v_pk_mul_f32 v[4:5], v[4:5], v[128:129]
	v_pk_mul_f32 v[2:3], v[2:3], v[126:127]

.LBB0_1109:
	s_waitcnt lgkmcnt(14)
	v_mfma_f32_32x32x16_bf16 v[50:65], v[166:169], v[210:213], v[50:65]
	v_exp_f32_e32 v130, v130
	v_exp_f32_e32 v131, v131
	v_exp_f32_e32 v132, v132
	v_exp_f32_e32 v133, v133
	s_waitcnt lgkmcnt(12)
	v_mfma_f32_32x32x16_bf16 v[34:49], v[166:169], v[206:209], v[34:49]
	v_exp_f32_e32 v134, v134
	v_exp_f32_e32 v135, v135
	v_exp_f32_e32 v136, v136
	v_exp_f32_e32 v137, v137
	v_add_u32_e32 v94, s47, v241
	ds_read_b128 v[206:209], v94
	ds_read_b128 v[198:201], v94 offset:4096
	s_waitcnt lgkmcnt(12)
	v_mfma_f32_32x32x16_bf16 v[50:65], v[162:165], v[98:101], v[50:65]
	v_exp_f32_e32 v138, v138
	v_exp_f32_e32 v139, v139
	v_exp_f32_e32 v140, v140
	v_exp_f32_e32 v141, v141
	v_xor_b32_e32 v94, 32, v94
	ds_read_b128 v[202:205], v94
	ds_read_b128 v[194:197], v94 offset:4096
	s_waitcnt lgkmcnt(12)
	v_mfma_f32_32x32x16_bf16 v[34:49], v[162:165], v[102:105], v[34:49]
	v_exp_f32_e32 v142, v142
	v_exp_f32_e32 v143, v143
	v_exp_f32_e32 v144, v144
	v_exp_f32_e32 v145, v145
	v_xor_b32_e32 v94, 0x60, v94
	ds_read_b128 v[190:193], v94
	ds_read_b128 v[186:189], v94 offset:4096
	s_waitcnt lgkmcnt(12)
	v_mfma_f32_32x32x16_bf16 v[50:65], v[158:161], v[106:109], v[50:65]
	v_exp_f32_e32 v114, v114
	v_exp_f32_e32 v115, v115
	v_exp_f32_e32 v116, v116
	v_exp_f32_e32 v117, v117
	v_xor_b32_e32 v94, 32, v94
	ds_read_b128 v[182:185], v94
	ds_read_b128 v[178:181], v94 offset:4096
	s_waitcnt lgkmcnt(12)
	v_mfma_f32_32x32x16_bf16 v[34:49], v[158:161], v[82:85], v[34:49]
	v_exp_f32_e32 v118, v118
	v_exp_f32_e32 v119, v119
	v_exp_f32_e32 v120, v120
	v_exp_f32_e32 v121, v121
	s_waitcnt lgkmcnt(10)
	v_mfma_f32_32x32x16_bf16 v[50:65], v[154:157], v[86:89], v[50:65]
	v_exp_f32_e32 v122, v122
	v_exp_f32_e32 v123, v123
	v_exp_f32_e32 v124, v124
	v_exp_f32_e32 v125, v125
	s_waitcnt lgkmcnt(8)
	v_mfma_f32_32x32x16_bf16 v[34:49], v[154:157], v[90:93], v[34:49]
	v_exp_f32_e32 v126, v126
	v_exp_f32_e32 v127, v127
	v_exp_f32_e32 v128, v128
	v_exp_f32_e32 v129, v129
	v_add_u32_e32 v98, s30, v245
	ds_read_b64_tr_b16 v[82:83],v98 offset:0
	ds_read_b64_tr_b16 v[84:85],v98 offset:512
	ds_read_b64_tr_b16 v[86:87],v98 offset:1024
	ds_read_b64_tr_b16 v[88:89],v98 offset:1536
	ds_read_b64_tr_b16 v[90:91],v98 offset:2048
	ds_read_b64_tr_b16 v[92:93],v98 offset:2560
	ds_read_b64_tr_b16 v[94:95],v98 offset:3072
	ds_read_b64_tr_b16 v[96:97],v98 offset:3584
	s_waitcnt lgkmcnt(0)
	s_nop 0
	v_mfma_f32_32x32x16_bf16 v[18:33], v[166:169], v[82:85], v[18:33]
	ds_read_b64_tr_b16 v[82:83],v98 offset:4096
	ds_read_b64_tr_b16 v[84:85],v98 offset:4608
	v_mfma_f32_32x32x16_bf16 v[18:33], v[162:165], v[86:89], v[18:33]
	ds_read_b64_tr_b16 v[86:87],v98 offset:5120
	ds_read_b64_tr_b16 v[88:89],v98 offset:5632
	v_mfma_f32_32x32x16_bf16 v[18:33], v[158:161], v[90:93], v[18:33]
	ds_read_b64_tr_b16 v[90:91],v98 offset:6144
	ds_read_b64_tr_b16 v[92:93],v98 offset:6656
	v_mfma_f32_32x32x16_bf16 v[18:33], v[154:157], v[94:97], v[18:33]
	ds_read_b64_tr_b16 v[94:95],v98 offset:7168
	ds_read_b64_tr_b16 v[96:97],v98 offset:7680
	s_waitcnt lgkmcnt(0)
	v_mfma_f32_32x32x16_bf16 v[2:17], v[166:169], v[82:85], v[2:17]
	s_mov_b64 s[4:5], -1
	s_and_b64 vcc, exec, s[16:17]
	v_mfma_f32_32x32x16_bf16 v[2:17], v[162:165], v[86:89], v[2:17]
	v_mfma_f32_32x32x16_bf16 v[2:17], v[158:161], v[90:93], v[2:17]
	v_mfma_f32_32x32x16_bf16 v[2:17], v[154:157], v[94:97], v[2:17]
	s_cbranch_vccz .LBB0_1142
	s_add_i32 s4, s50, -2
	s_cmp_ge_i32 s4, s48
	s_mov_b64 s[4:5], -1
	s_cbranch_scc0 .LBB0_1112
	s_waitcnt vmcnt(0) lgkmcnt(0)
	s_barrier
	s_mov_b64 s[4:5], 0

.LBB0_1124:
	s_waitcnt lgkmcnt(14)
	v_mfma_f32_32x32x16_bf16 v[50:65], v[166:169], v[218:221], v[50:65]
	v_exp_f32_e32 v98, v98
	v_exp_f32_e32 v99, v99
	v_exp_f32_e32 v100, v100
	v_exp_f32_e32 v101, v101
	s_waitcnt lgkmcnt(12)
	v_mfma_f32_32x32x16_bf16 v[34:49], v[166:169], v[214:217], v[34:49]
	v_exp_f32_e32 v102, v102
	v_exp_f32_e32 v103, v103
	v_exp_f32_e32 v104, v104
	v_exp_f32_e32 v105, v105
	v_cndmask_b32_e64 v122, 0, 1, s[36:37]
	v_cmp_ne_u32_e64 s[4:5], 1, v122
	s_andn2_b64 vcc, exec, s[36:37]
	v_add_u32_e32 v122, s40, v241
	s_cbranch_vccnz .LBB0_1126
	ds_read_b128 v[206:209], v122
	ds_read_b128 v[198:201], v122 offset:4096
.LBB0_1126:
	s_waitcnt lgkmcnt(10)
	v_mfma_f32_32x32x16_bf16 v[50:65], v[162:165], v[210:213], v[50:65]
	v_exp_f32_e32 v106, v106
	v_exp_f32_e32 v107, v107
	v_exp_f32_e32 v108, v108
	v_exp_f32_e32 v109, v109
	s_and_b64 vcc, exec, s[4:5]
	s_cbranch_vccnz .LBB0_1128
	v_xor_b32_e32 v122, 32, v122
	ds_read_b128 v[202:205], v122
	ds_read_b128 v[194:197], v122 offset:4096
.LBB0_1128:
	s_waitcnt lgkmcnt(8)
	v_mfma_f32_32x32x16_bf16 v[34:49], v[162:165], v[138:141], v[34:49]
	v_exp_f32_e32 v110, v110
	v_exp_f32_e32 v111, v111
	v_exp_f32_e32 v112, v112
	v_exp_f32_e32 v113, v113
	s_and_b64 vcc, exec, s[4:5]
	s_cbranch_vccnz .LBB0_1130
	v_xor_b32_e32 v122, 0x60, v122
	ds_read_b128 v[190:193], v122
	ds_read_b128 v[186:189], v122 offset:4096
.LBB0_1130:
	s_waitcnt lgkmcnt(6)
	v_mfma_f32_32x32x16_bf16 v[50:65], v[158:161], v[134:137], v[50:65]
	v_exp_f32_e32 v82, v82
	v_exp_f32_e32 v83, v83
	v_exp_f32_e32 v84, v84
	v_exp_f32_e32 v85, v85
	s_and_b64 vcc, exec, s[4:5]
	s_cbranch_vccnz .LBB0_1132
	v_xor_b32_e32 v122, 32, v122
	ds_read_b128 v[182:185], v122
	ds_read_b128 v[178:181], v122 offset:4096
